# P0 norm loop rewritten (4-deep pipelined, wave-uniform) + nt on cold streaming loads (P0 rows, weight transposes, sample states)
# speedup vs baseline: 1.0147x; 1.0147x over previous
; #define LAS __attribute__((address_space(3)))
; DI void tr_weight(const float* W, bf16_t* Wt, const int K, const int N, const int ntn, const int drow_off, const int gu, const int rot, ldsp lds, int tid, const int G, const int lb) {
;   LAS float* tile = (LAS float*)lds;
;   const int nn = tid & 63, kb = tid >> 6, n2 = tid >> 3, kq = tid & 7;
;   const int ktiles = K / 64, ntiles = ntn * ktiles;
;   int task = (lb + G - (rot % G)) % G;
;   float pre[8];
;   if (task < ntiles) { const int n = (task / ktiles) * 64 + nn, k0 = (task % ktiles) * 64;
; #pragma unroll
;     for (int i = 0; i < 8; ++i) pre[i] = (n < N) ? W[(size_t)(k0 + kb + 8 * i) * N + n] : 0.f; }
.LBB0_17:
	s_or_b64 exec, exec, s[4:5]
	s_abs_i32 s0, s94
	v_cvt_f32_u32_e32 v0, s0
	s_sub_i32 s3, 0, s0
	s_add_i32 s1, s94, s2
	s_abs_i32 s5, s1
	v_rcp_iflag_f32_e32 v0, v0
	s_ashr_i32 s4, s1, 31
	v_mov_b32_e32 v15, v212
	v_mul_f32_e32 v0, 0x4f7ffffe, v0
	v_cvt_u32_f32_e32 v0, v0
	s_barrier
	v_readfirstlane_b32 s6, v0
	s_mul_i32 s3, s3, s6
	s_mul_hi_u32 s3, s6, s3
	s_add_i32 s3, s6, s3
	s_mul_hi_u32 s6, s5, s3
	s_mul_i32 s6, s6, s0
	s_sub_i32 s5, s5, s6
	s_sub_i32 s6, s5, s0
	s_cmp_ge_u32 s5, s0
	s_cselect_b32 s5, s6, s5
	s_sub_i32 s6, s5, s0
	s_cmp_ge_u32 s5, s0
	s_cselect_b32 s5, s6, s5
	s_xor_b32 s5, s5, s4
	s_sub_i32 s10, s5, s4
	v_ashrrev_i32_e32 v14, 6, v15
	v_and_b32_e32 v34, 63, v15
	s_cmpk_lt_i32 s10, 0x340
	v_ashrrev_i32_e32 v16, 3, v15
	s_cbranch_scc0 .LBB0_54
	s_ashr_i32 s6, s10, 31
	s_lshr_b32 s6, s6, 28
	s_load_dwordx2 s[4:5], s[72:73], 0x50
	s_add_i32 s6, s10, s6
	s_lshl_b32 s7, s6, 2
	s_andn2_b32 s7, s7, 63
	v_or_b32_e32 v0, s7, v34
	s_and_b32 s6, s6, 0x3fffff0
	s_sub_i32 s6, s10, s6
	s_movk_i32 s7, 0xc18
	v_ashrrev_i32_e32 v1, 31, v0
	v_cmp_gt_i32_e32 vcc, s7, v0
	v_lshl_add_u32 v10, s6, 6, v14
	s_waitcnt lgkmcnt(0)
	v_lshl_add_u64 v[8:9], v[0:1], 2, s[4:5]
	v_mov_b32_e32 v1, 0
	v_mov_b32_e32 v0, 0
	s_and_saveexec_b64 s[6:7], vcc
	s_cbranch_execz .LBB0_20
	s_movk_i32 s8, 0x3060
	v_mad_i64_i32 v[2:3], s[8:9], v10, s8, v[8:9]
	global_load_dword v0, v[2:3], off nt
.LBB0_20:
	s_or_b64 exec, exec, s[6:7]
	s_and_saveexec_b64 s[6:7], vcc
	s_cbranch_execz .LBB0_22
	v_add_u32_e32 v1, 8, v10
	s_movk_i32 s8, 0x3060
	v_mad_i64_i32 v[2:3], s[8:9], v1, s8, v[8:9]
	global_load_dword v1, v[2:3], off nt
.LBB0_22:
	s_or_b64 exec, exec, s[6:7]
	v_mov_b32_e32 v3, 0
	v_mov_b32_e32 v2, 0
	s_and_saveexec_b64 s[6:7], vcc
	s_cbranch_execz .LBB0_24
	v_add_u32_e32 v2, 16, v10
	s_movk_i32 s8, 0x3060
	v_mad_i64_i32 v[4:5], s[8:9], v2, s8, v[8:9]
	global_load_dword v2, v[4:5], off nt
.LBB0_24:
	s_or_b64 exec, exec, s[6:7]
	s_and_saveexec_b64 s[6:7], vcc
	s_cbranch_execz .LBB0_26
	v_add_u32_e32 v3, 24, v10
	s_movk_i32 s8, 0x3060
	v_mad_i64_i32 v[4:5], s[8:9], v3, s8, v[8:9]
	global_load_dword v3, v[4:5], off nt
.LBB0_26:
	s_or_b64 exec, exec, s[6:7]
	v_mov_b32_e32 v5, 0
	v_mov_b32_e32 v4, 0
	s_and_saveexec_b64 s[6:7], vcc
	s_cbranch_execz .LBB0_28
	v_add_u32_e32 v4, 32, v10
	s_movk_i32 s8, 0x3060
	v_mad_i64_i32 v[6:7], s[8:9], v4, s8, v[8:9]
	global_load_dword v4, v[6:7], off nt
.LBB0_28:
	s_or_b64 exec, exec, s[6:7]
	s_and_saveexec_b64 s[6:7], vcc
	s_cbranch_execz .LBB0_30
	v_add_u32_e32 v5, 40, v10
	s_movk_i32 s8, 0x3060
	v_mad_i64_i32 v[6:7], s[8:9], v5, s8, v[8:9]
	global_load_dword v5, v[6:7], off nt
.LBB0_30:
	s_or_b64 exec, exec, s[6:7]
	v_mov_b32_e32 v7, 0
	v_mov_b32_e32 v6, 0
	s_and_saveexec_b64 s[6:7], vcc
	s_cbranch_execz .LBB0_32
	v_add_u32_e32 v6, 48, v10
	s_movk_i32 s8, 0x3060
	v_mad_i64_i32 v[12:13], s[8:9], v6, s8, v[8:9]
	global_load_dword v6, v[12:13], off nt
.LBB0_32:
	s_or_b64 exec, exec, s[6:7]
	s_and_saveexec_b64 s[6:7], vcc
	s_cbranch_execz .LBB0_34
	v_add_u32_e32 v7, 56, v10
	s_movk_i32 s8, 0x3060
	v_mad_i64_i32 v[8:9], s[8:9], v7, s8, v[8:9]
	global_load_dword v7, v[8:9], off nt

; DI void tr_weight(const float* W, bf16_t* Wt, const int K, const int N, const int ntn, const int drow_off, const int gu, const int rot, ldsp lds, int tid, const int G, const int lb) {
;     ...
;   int task = (lb + G - (rot % G)) % G;
;   float pre[8];
;   if (task < ntiles) { const int n = (task / ktiles) * 64 + nn, k0 = (task % ktiles) * 64;
; #pragma unroll
;     for (int i = 0; i < 8; ++i) pre[i] = (n < N) ? W[(size_t)(k0 + kb + 8 * i) * N + n] : 0.f; }
;   while (task < ntiles) {
; #pragma unroll
;     for (int i = 0; i < 8; ++i) tile[(kb + 8 * i) * 65 + nn] = pre[i];
;     const int n0 = (task / ktiles) * 64, k0 = (task % ktiles) * 64;
;     const int nxt = task + G;
;     if (nxt < ntiles) { const int n = (nxt / ktiles) * 64 + nn, k1 = (nxt % ktiles) * 64;
; #pragma unroll
;       for (int i = 0; i < 8; ++i) pre[i] = (n < N) ? W[(size_t)(k1 + kb + 8 * i) * N + n] : 0.f; }
.LBB0_37:
	s_add_i32 s15, s10, s94
	s_cmpk_gt_i32 s15, 0x33f
	s_cselect_b64 s[6:7], -1, 0
	s_and_b64 vcc, exec, s[6:7]
	s_waitcnt vmcnt(0)
	ds_write_b32 v13, v0
	ds_write_b32 v13, v1 offset:2080
	ds_write_b32 v13, v2 offset:4160
	ds_write_b32 v13, v3 offset:6240
	ds_write_b32 v13, v4 offset:8320
	ds_write_b32 v13, v5 offset:10400
	ds_write_b32 v13, v6 offset:12480
	ds_write_b32 v13, v7 offset:14560
	s_cbranch_vccnz .LBB0_36
	s_ashr_i32 s8, s15, 31
	s_lshr_b32 s8, s8, 28
	s_add_i32 s8, s15, s8
	s_ashr_i32 s8, s8, 4
	v_lshl_or_b32 v0, s8, 6, v34
	v_add_u32_e32 v1, s11, v12
	s_lshl_b32 s8, s8, 10
	v_subrev_u32_e32 v18, s8, v1
	v_ashrrev_i32_e32 v1, 31, v0
	v_cmp_gt_i32_e32 vcc, s13, v0
	v_lshl_add_u64 v[10:11], v[0:1], 2, s[4:5]
	v_mov_b32_e32 v1, 0
	v_mov_b32_e32 v0, 0
	s_and_saveexec_b64 s[8:9], vcc
	s_cbranch_execz .LBB0_40
	v_mad_i64_i32 v[2:3], s[16:17], v18, s14, v[10:11]
	global_load_dword v0, v[2:3], off nt
.LBB0_40:
	s_or_b64 exec, exec, s[8:9]
	s_and_saveexec_b64 s[8:9], vcc
	s_cbranch_execz .LBB0_42
	v_add_u32_e32 v1, 8, v18
	v_mad_i64_i32 v[2:3], s[16:17], v1, s14, v[10:11]
	global_load_dword v1, v[2:3], off nt
.LBB0_42:
	s_or_b64 exec, exec, s[8:9]
	v_mov_b32_e32 v3, 0
	v_mov_b32_e32 v2, 0
	s_and_saveexec_b64 s[8:9], vcc
	s_cbranch_execz .LBB0_44
	v_add_u32_e32 v2, 16, v18
	v_mad_i64_i32 v[4:5], s[16:17], v2, s14, v[10:11]
	global_load_dword v2, v[4:5], off nt
.LBB0_44:
	s_or_b64 exec, exec, s[8:9]
	s_and_saveexec_b64 s[8:9], vcc
	s_cbranch_execz .LBB0_46
	v_add_u32_e32 v3, 24, v18
	v_mad_i64_i32 v[4:5], s[16:17], v3, s14, v[10:11]
	global_load_dword v3, v[4:5], off nt
.LBB0_46:
	s_or_b64 exec, exec, s[8:9]
	v_mov_b32_e32 v5, 0
	v_mov_b32_e32 v4, 0
	s_and_saveexec_b64 s[8:9], vcc
	s_cbranch_execz .LBB0_48
	v_add_u32_e32 v4, 32, v18
	v_mad_i64_i32 v[6:7], s[16:17], v4, s14, v[10:11]
	global_load_dword v4, v[6:7], off nt
.LBB0_48:
	s_or_b64 exec, exec, s[8:9]
	s_and_saveexec_b64 s[8:9], vcc
	s_cbranch_execz .LBB0_50
	v_add_u32_e32 v5, 40, v18
	v_mad_i64_i32 v[6:7], s[16:17], v5, s14, v[10:11]
	global_load_dword v5, v[6:7], off nt
.LBB0_50:
	s_or_b64 exec, exec, s[8:9]
	v_mov_b32_e32 v7, 0
	v_mov_b32_e32 v6, 0
	s_and_saveexec_b64 s[8:9], vcc
	s_cbranch_execz .LBB0_52
	v_add_u32_e32 v6, 48, v18
	v_mad_i64_i32 v[20:21], s[16:17], v6, s14, v[10:11]
	global_load_dword v6, v[20:21], off nt
.LBB0_52:
	s_or_b64 exec, exec, s[8:9]
	s_and_saveexec_b64 s[8:9], vcc
	s_cbranch_execz .LBB0_35
	v_add_u32_e32 v7, 56, v18
	v_mad_i64_i32 v[10:11], s[16:17], v7, s14, v[10:11]
	global_load_dword v7, v[10:11], off nt
	s_branch .LBB0_35
.LBB0_54:
	s_mul_hi_u32 s4, s3, 0x340
	s_add_u32 s6, s42, 0x680000
	s_mul_i32 s4, s4, s0
	s_addc_u32 s7, s43, 0
	s_sub_i32 s4, 0x340, s4
	s_sub_i32 s5, s4, s0
	s_cmp_ge_u32 s4, s0
	s_cselect_b32 s4, s5, s4
	s_sub_i32 s5, s4, s0
	s_cmp_ge_u32 s4, s0
	s_cselect_b32 s4, s5, s4
	s_sub_i32 s4, s1, s4
	s_ashr_i32 s5, s4, 31
	s_abs_i32 s4, s4
	s_mul_hi_u32 s12, s4, s3
	s_mul_i32 s12, s12, s0
	s_sub_i32 s4, s4, s12
	s_sub_i32 s12, s4, s0
	s_cmp_ge_u32 s4, s0
	s_cselect_b32 s4, s12, s4
	s_sub_i32 s12, s4, s0
	s_load_dwordx4 s[8:11], s[72:73], 0xc8
	s_cmp_ge_u32 s4, s0
	s_cselect_b32 s4, s12, s4
	s_xor_b32 s4, s4, s5
	s_sub_i32 s14, s4, s5
	s_cmpk_gt_i32 s14, 0xff
	s_cbranch_scc1 .LBB0_91
	s_ashr_i32 s4, s14, 31
	s_lshr_b32 s4, s4, 28
	s_add_i32 s4, s14, s4
	s_lshl_b32 s5, s4, 2
	s_andn2_b32 s5, s5, 63
	s_and_b32 s4, s4, 0x3fffff0
	s_waitcnt vmcnt(1)
	v_or_b32_e32 v0, s5, v34
	s_sub_i32 s12, s14, s4
	s_movk_i32 s4, 0x400
	v_lshl_add_u32 v8, s12, 6, v14
	v_ashrrev_i32_e32 v1, 31, v0
	v_cmp_gt_i32_e64 s[4:5], s4, v0
	s_waitcnt lgkmcnt(0)
	v_lshl_add_u64 v[10:11], v[0:1], 2, s[8:9]
	v_mov_b32_e32 v1, 0
	v_ashrrev_i32_e32 v9, 31, v8
	v_mov_b32_e32 v0, 0
	s_and_saveexec_b64 s[12:13], s[4:5]
	s_cbranch_execz .LBB0_57
	v_lshlrev_b64 v[2:3], 12, v[8:9]
	v_lshl_add_u64 v[2:3], v[10:11], 0, v[2:3]
	global_load_dword v0, v[2:3], off nt
.LBB0_57:
	s_or_b64 exec, exec, s[12:13]
	s_and_saveexec_b64 s[12:13], s[4:5]
	s_cbranch_execz .LBB0_59
	v_lshlrev_b64 v[2:3], 12, v[8:9]
	v_lshl_add_u64 v[2:3], v[10:11], 0, v[2:3]
	v_add_co_u32_e32 v2, vcc, 0x8000, v2
	s_nop 1
	v_addc_co_u32_e32 v3, vcc, 0, v3, vcc
	global_load_dword v1, v[2:3], off nt
.LBB0_59:
	s_or_b64 exec, exec, s[12:13]
	v_mov_b32_e32 v3, 0
	v_mov_b32_e32 v2, 0
	s_and_saveexec_b64 s[12:13], s[4:5]
	s_cbranch_execz .LBB0_61
	v_lshlrev_b64 v[4:5], 12, v[8:9]
	v_lshl_add_u64 v[4:5], v[10:11], 0, v[4:5]
	v_add_co_u32_e32 v4, vcc, 0x10000, v4
	s_nop 1
	v_addc_co_u32_e32 v5, vcc, 0, v5, vcc
	global_load_dword v2, v[4:5], off nt
.LBB0_61:
	s_or_b64 exec, exec, s[12:13]
	s_and_saveexec_b64 s[12:13], s[4:5]
	s_cbranch_execz .LBB0_63
	v_lshlrev_b64 v[4:5], 12, v[8:9]
	v_lshl_add_u64 v[4:5], v[10:11], 0, v[4:5]
	v_add_co_u32_e32 v4, vcc, 0x18000, v4
	s_nop 1
	v_addc_co_u32_e32 v5, vcc, 0, v5, vcc
	global_load_dword v3, v[4:5], off nt
.LBB0_63:
	s_or_b64 exec, exec, s[12:13]
	v_mov_b32_e32 v5, 0
	v_mov_b32_e32 v4, 0
	s_and_saveexec_b64 s[12:13], s[4:5]
	s_cbranch_execz .LBB0_65
	v_lshlrev_b64 v[6:7], 12, v[8:9]
	v_lshl_add_u64 v[6:7], v[10:11], 0, v[6:7]
	v_add_co_u32_e32 v6, vcc, 0x20000, v6
	s_nop 1
	v_addc_co_u32_e32 v7, vcc, 0, v7, vcc
	global_load_dword v4, v[6:7], off nt
.LBB0_65:
	s_or_b64 exec, exec, s[12:13]
	s_and_saveexec_b64 s[12:13], s[4:5]
	s_cbranch_execz .LBB0_67
	v_lshlrev_b64 v[6:7], 12, v[8:9]
	v_lshl_add_u64 v[6:7], v[10:11], 0, v[6:7]
	v_add_co_u32_e32 v6, vcc, 0x28000, v6
	s_nop 1
	v_addc_co_u32_e32 v7, vcc, 0, v7, vcc
	global_load_dword v5, v[6:7], off nt
.LBB0_67:
	s_or_b64 exec, exec, s[12:13]
	v_mov_b32_e32 v7, 0
	v_mov_b32_e32 v6, 0
	s_and_saveexec_b64 s[12:13], s[4:5]
	s_cbranch_execz .LBB0_69
	v_lshlrev_b64 v[12:13], 12, v[8:9]
	v_lshl_add_u64 v[12:13], v[10:11], 0, v[12:13]
	v_add_co_u32_e32 v12, vcc, 0x30000, v12
	s_nop 1
	v_addc_co_u32_e32 v13, vcc, 0, v13, vcc
	global_load_dword v6, v[12:13], off nt
.LBB0_69:
	s_or_b64 exec, exec, s[12:13]
	s_and_saveexec_b64 s[12:13], s[4:5]
	s_cbranch_execz .LBB0_71
	v_lshlrev_b64 v[8:9], 12, v[8:9]
	v_lshl_add_u64 v[8:9], v[10:11], 0, v[8:9]
	v_add_co_u32_e32 v8, vcc, 0x38000, v8
	s_nop 1
	v_addc_co_u32_e32 v9, vcc, 0, v9, vcc
	global_load_dword v7, v[8:9], off nt

; DI void tr_weight(const float* W, bf16_t* Wt, const int K, const int N, const int ntn, const int drow_off, const int gu, const int rot, ldsp lds, int tid, const int G, const int lb) {
;     ...
;   int task = (lb + G - (rot % G)) % G;
;   float pre[8];
;   if (task < ntiles) { const int n = (task / ktiles) * 64 + nn, k0 = (task % ktiles) * 64;
; #pragma unroll
;     for (int i = 0; i < 8; ++i) pre[i] = (n < N) ? W[(size_t)(k0 + kb + 8 * i) * N + n] : 0.f; }
;   while (task < ntiles) {
; #pragma unroll
;     for (int i = 0; i < 8; ++i) tile[(kb + 8 * i) * 65 + nn] = pre[i];
;     const int n0 = (task / ktiles) * 64, k0 = (task % ktiles) * 64;
;     const int nxt = task + G;
;     if (nxt < ntiles) { const int n = (nxt / ktiles) * 64 + nn, k1 = (nxt % ktiles) * 64;
; #pragma unroll
;       for (int i = 0; i < 8; ++i) pre[i] = (n < N) ? W[(size_t)(k1 + kb + 8 * i) * N + n] : 0.f; }
.LBB0_74:
	s_add_i32 s18, s14, s94
	s_cmpk_gt_i32 s18, 0xff
	s_cselect_b64 s[4:5], -1, 0
	s_and_b64 vcc, exec, s[4:5]
	s_waitcnt vmcnt(0)
	ds_write_b32 v18, v0
	ds_write_b32 v18, v1 offset:2080
	ds_write_b32 v18, v2 offset:4160
	ds_write_b32 v18, v3 offset:6240
	ds_write_b32 v18, v4 offset:8320
	ds_write_b32 v18, v5 offset:10400
	ds_write_b32 v18, v6 offset:12480
	ds_write_b32 v18, v7 offset:14560
	s_cbranch_vccnz .LBB0_73
	s_ashr_i32 s12, s18, 31
	s_lshr_b32 s12, s12, 28
	s_add_i32 s12, s18, s12
	s_ashr_i32 s12, s12, 4
	v_lshl_or_b32 v0, s12, 6, v34
	v_add_u32_e32 v1, s15, v17
	s_lshl_b32 s12, s12, 10
	v_subrev_u32_e32 v12, s12, v1
	v_ashrrev_i32_e32 v1, 31, v0
	v_cmp_gt_i32_e32 vcc, s17, v0
	v_lshl_add_u64 v[10:11], v[0:1], 2, s[8:9]
	v_mov_b32_e32 v1, 0
	v_mov_b32_e32 v0, 0
	s_and_saveexec_b64 s[12:13], vcc
	s_cbranch_execz .LBB0_77
	v_ashrrev_i32_e32 v13, 31, v12
	v_lshlrev_b64 v[2:3], 12, v[12:13]
	v_lshl_add_u64 v[2:3], v[10:11], 0, v[2:3]
	global_load_dword v0, v[2:3], off nt
.LBB0_77:
	s_or_b64 exec, exec, s[12:13]
	s_and_saveexec_b64 s[12:13], vcc
	s_cbranch_execz .LBB0_79
	v_add_u32_e32 v2, 8, v12
	v_ashrrev_i32_e32 v3, 31, v2
	v_lshlrev_b64 v[2:3], 12, v[2:3]
	v_lshl_add_u64 v[2:3], v[10:11], 0, v[2:3]
	global_load_dword v1, v[2:3], off nt
.LBB0_79:
	s_or_b64 exec, exec, s[12:13]
	v_mov_b32_e32 v3, 0
	v_mov_b32_e32 v2, 0
	s_and_saveexec_b64 s[12:13], vcc
	s_cbranch_execz .LBB0_81
	v_add_u32_e32 v4, 16, v12
	v_ashrrev_i32_e32 v5, 31, v4
	v_lshlrev_b64 v[4:5], 12, v[4:5]
	v_lshl_add_u64 v[4:5], v[10:11], 0, v[4:5]
	global_load_dword v2, v[4:5], off nt
.LBB0_81:
	s_or_b64 exec, exec, s[12:13]
	s_and_saveexec_b64 s[12:13], vcc
	s_cbranch_execz .LBB0_83
	v_add_u32_e32 v4, 24, v12
	v_ashrrev_i32_e32 v5, 31, v4
	v_lshlrev_b64 v[4:5], 12, v[4:5]
	v_lshl_add_u64 v[4:5], v[10:11], 0, v[4:5]
	global_load_dword v3, v[4:5], off nt
.LBB0_83:
	s_or_b64 exec, exec, s[12:13]
	v_mov_b32_e32 v5, 0
	v_mov_b32_e32 v4, 0
	s_and_saveexec_b64 s[12:13], vcc
	s_cbranch_execz .LBB0_85
	v_add_u32_e32 v6, 32, v12
	v_ashrrev_i32_e32 v7, 31, v6
	v_lshlrev_b64 v[6:7], 12, v[6:7]
	v_lshl_add_u64 v[6:7], v[10:11], 0, v[6:7]
	global_load_dword v4, v[6:7], off nt
.LBB0_85:
	s_or_b64 exec, exec, s[12:13]
	s_and_saveexec_b64 s[12:13], vcc
	s_cbranch_execz .LBB0_87
	v_add_u32_e32 v6, 40, v12
	v_ashrrev_i32_e32 v7, 31, v6
	v_lshlrev_b64 v[6:7], 12, v[6:7]
	v_lshl_add_u64 v[6:7], v[10:11], 0, v[6:7]
	global_load_dword v5, v[6:7], off nt
.LBB0_87:
	s_or_b64 exec, exec, s[12:13]
	v_mov_b32_e32 v7, 0
	v_mov_b32_e32 v6, 0
	s_and_saveexec_b64 s[12:13], vcc
	s_cbranch_execz .LBB0_89
	v_add_u32_e32 v20, 48, v12
	v_ashrrev_i32_e32 v21, 31, v20
	v_lshlrev_b64 v[20:21], 12, v[20:21]
	v_lshl_add_u64 v[20:21], v[10:11], 0, v[20:21]
	global_load_dword v6, v[20:21], off nt
.LBB0_89:
	s_or_b64 exec, exec, s[12:13]
	s_and_saveexec_b64 s[12:13], vcc
	s_cbranch_execz .LBB0_72
	v_add_u32_e32 v12, 56, v12
	v_ashrrev_i32_e32 v13, 31, v12
	v_lshlrev_b64 v[12:13], 12, v[12:13]
	v_lshl_add_u64 v[10:11], v[10:11], 0, v[12:13]
	global_load_dword v7, v[10:11], off nt
	s_branch .LBB0_72
.LBB0_91:
	s_mul_hi_u32 s4, s3, 0x440
	s_mul_i32 s4, s4, s0
	s_sub_i32 s4, 0x440, s4
	s_sub_i32 s5, s4, s0
	s_cmp_ge_u32 s4, s0
	s_cselect_b32 s4, s5, s4
	s_sub_i32 s5, s4, s0
	s_cmp_ge_u32 s4, s0
	s_cselect_b32 s4, s5, s4
	s_sub_i32 s1, s1, s4
	s_ashr_i32 s4, s1, 31
	s_abs_i32 s1, s1
	s_mul_hi_u32 s3, s1, s3
	s_mul_i32 s3, s3, s0
	s_sub_i32 s1, s1, s3
	s_sub_i32 s3, s1, s0
	s_cmp_ge_u32 s1, s0
	s_cselect_b32 s1, s3, s1
	s_sub_i32 s3, s1, s0
	s_cmp_ge_u32 s1, s0
	s_cselect_b32 s0, s3, s1
	s_xor_b32 s0, s0, s4
	s_sub_i32 s0, s0, s4
	s_cmpk_gt_i32 s0, 0xff
	s_cbranch_scc1 .LBB0_128
	s_ashr_i32 s1, s0, 31
	s_lshr_b32 s1, s1, 28
	s_add_i32 s1, s0, s1
	s_lshl_b32 s3, s1, 2
	s_andn2_b32 s3, s3, 63
	s_and_b32 s1, s1, 0x3fffff0
	s_waitcnt vmcnt(1)
	v_or_b32_e32 v0, s3, v34
	s_sub_i32 s1, s0, s1
	s_movk_i32 s3, 0x400
	v_lshl_add_u32 v8, s1, 6, v14
	v_ashrrev_i32_e32 v1, 31, v0
	v_cmp_gt_i32_e64 s[4:5], s3, v0
	s_waitcnt lgkmcnt(0)
	v_lshl_add_u64 v[10:11], v[0:1], 2, s[10:11]
	v_mov_b32_e32 v1, 0
	v_ashrrev_i32_e32 v9, 31, v8
	v_mov_b32_e32 v0, 0
	s_and_saveexec_b64 s[8:9], s[4:5]
	s_cbranch_execz .LBB0_94
	v_lshlrev_b64 v[2:3], 12, v[8:9]
	v_lshl_add_u64 v[2:3], v[10:11], 0, v[2:3]
	global_load_dword v0, v[2:3], off nt
.LBB0_94:
	s_or_b64 exec, exec, s[8:9]
	s_and_saveexec_b64 s[8:9], s[4:5]
	s_cbranch_execz .LBB0_96
	v_lshlrev_b64 v[2:3], 12, v[8:9]
	v_lshl_add_u64 v[2:3], v[10:11], 0, v[2:3]
	v_add_co_u32_e32 v2, vcc, 0x8000, v2
	s_nop 1
	v_addc_co_u32_e32 v3, vcc, 0, v3, vcc
	global_load_dword v1, v[2:3], off nt
.LBB0_96:
	s_or_b64 exec, exec, s[8:9]
	v_mov_b32_e32 v3, 0
	v_mov_b32_e32 v2, 0
	s_and_saveexec_b64 s[8:9], s[4:5]
	s_cbranch_execz .LBB0_98
	v_lshlrev_b64 v[4:5], 12, v[8:9]
	v_lshl_add_u64 v[4:5], v[10:11], 0, v[4:5]
	v_add_co_u32_e32 v4, vcc, 0x10000, v4
	s_nop 1
	v_addc_co_u32_e32 v5, vcc, 0, v5, vcc
	global_load_dword v2, v[4:5], off nt
.LBB0_98:
	s_or_b64 exec, exec, s[8:9]
	s_and_saveexec_b64 s[8:9], s[4:5]
	s_cbranch_execz .LBB0_100
	v_lshlrev_b64 v[4:5], 12, v[8:9]
	v_lshl_add_u64 v[4:5], v[10:11], 0, v[4:5]
	v_add_co_u32_e32 v4, vcc, 0x18000, v4
	s_nop 1
	v_addc_co_u32_e32 v5, vcc, 0, v5, vcc
	global_load_dword v3, v[4:5], off nt
.LBB0_100:
	s_or_b64 exec, exec, s[8:9]
	v_mov_b32_e32 v5, 0
	v_mov_b32_e32 v4, 0
	s_and_saveexec_b64 s[8:9], s[4:5]
	s_cbranch_execz .LBB0_102
	v_lshlrev_b64 v[6:7], 12, v[8:9]
	v_lshl_add_u64 v[6:7], v[10:11], 0, v[6:7]
	v_add_co_u32_e32 v6, vcc, 0x20000, v6
	s_nop 1
	v_addc_co_u32_e32 v7, vcc, 0, v7, vcc
	global_load_dword v4, v[6:7], off nt
.LBB0_102:
	s_or_b64 exec, exec, s[8:9]
	s_and_saveexec_b64 s[8:9], s[4:5]
	s_cbranch_execz .LBB0_104
	v_lshlrev_b64 v[6:7], 12, v[8:9]
	v_lshl_add_u64 v[6:7], v[10:11], 0, v[6:7]
	v_add_co_u32_e32 v6, vcc, 0x28000, v6
	s_nop 1
	v_addc_co_u32_e32 v7, vcc, 0, v7, vcc
	global_load_dword v5, v[6:7], off nt
.LBB0_104:
	s_or_b64 exec, exec, s[8:9]
	v_mov_b32_e32 v7, 0
	v_mov_b32_e32 v6, 0
	s_and_saveexec_b64 s[8:9], s[4:5]
	s_cbranch_execz .LBB0_106
	v_lshlrev_b64 v[12:13], 12, v[8:9]
	v_lshl_add_u64 v[12:13], v[10:11], 0, v[12:13]
	v_add_co_u32_e32 v12, vcc, 0x30000, v12
	s_nop 1
	v_addc_co_u32_e32 v13, vcc, 0, v13, vcc
	global_load_dword v6, v[12:13], off nt
.LBB0_106:
	s_or_b64 exec, exec, s[8:9]
	s_and_saveexec_b64 s[8:9], s[4:5]
	s_cbranch_execz .LBB0_108
	v_lshlrev_b64 v[8:9], 12, v[8:9]
	v_lshl_add_u64 v[8:9], v[10:11], 0, v[8:9]
	v_add_co_u32_e32 v8, vcc, 0x38000, v8
	s_nop 1
	v_addc_co_u32_e32 v9, vcc, 0, v9, vcc
	global_load_dword v7, v[8:9], off nt

; DI void tr_weight(const float* W, bf16_t* Wt, const int K, const int N, const int ntn, const int drow_off, const int gu, const int rot, ldsp lds, int tid, const int G, const int lb) {
;     ...
;   while (task < ntiles) {
; #pragma unroll
;     for (int i = 0; i < 8; ++i) tile[(kb + 8 * i) * 65 + nn] = pre[i];
;     const int n0 = (task / ktiles) * 64, k0 = (task % ktiles) * 64;
;     const int nxt = task + G;
;     if (nxt < ntiles) { const int n = (nxt / ktiles) * 64 + nn, k1 = (nxt % ktiles) * 64;
; #pragma unroll
;       for (int i = 0; i < 8; ++i) pre[i] = (n < N) ? W[(size_t)(k1 + kb + 8 * i) * N + n] : 0.f; }
; DI void phase_prep(const Params& p, ldsp lds, int tid_) {
;     ...
;   {
;     const int wv = blockIdx.x * 8 + wid, nwv = G * 8, NR = T + 2048;
;     f32x4 v0[4], v1[4];
;     const int r1 = wv + nwv;
;     if (wv < NR) {
; #pragma unroll
;       for (int i = 0; i < 4; ++i) v0[i] = *(const f32x4*)(prep_row_src(p, wv) + RCOL(i)); }
;     if (r1 < NR) {
; #pragma unroll
;       for (int i = 0; i < 4; ++i) v1[i] = *(const f32x4*)(prep_row_src(p, r1) + RCOL(i)); }
;     for (int r = wv; r < NR; r += nwv) {
;       const int rn = r + 2 * nwv; f32x4 v2[4];
;       const int rc = rn < NR ? rn : r;
; #pragma unroll
;       for (int i = 0; i < 4; ++i) v2[i] = *(const f32x4*)(prep_row_src(p, rc) + RCOL(i));
.LBB0_111:
	s_add_i32 s13, s0, s94
	s_cmpk_gt_i32 s13, 0xff
	s_cselect_b64 s[4:5], -1, 0
	s_and_b64 vcc, exec, s[4:5]
	s_waitcnt vmcnt(0)
	ds_write_b32 v17, v0
	ds_write_b32 v17, v1 offset:2080
	ds_write_b32 v17, v2 offset:4160
	ds_write_b32 v17, v3 offset:6240
	ds_write_b32 v17, v4 offset:8320
	ds_write_b32 v17, v5 offset:10400
	ds_write_b32 v17, v6 offset:12480
	ds_write_b32 v17, v7 offset:14560
	s_cbranch_vccnz .LBB0_110
	s_ashr_i32 s8, s13, 31
	s_lshr_b32 s8, s8, 28
	s_add_i32 s8, s13, s8
	s_ashr_i32 s8, s8, 4
	v_lshl_or_b32 v0, s8, 6, v34
	v_add_u32_e32 v1, s3, v16
	s_lshl_b32 s8, s8, 10
	v_subrev_u32_e32 v12, s8, v1
	v_ashrrev_i32_e32 v1, 31, v0
	v_cmp_gt_i32_e32 vcc, s1, v0
	v_lshl_add_u64 v[10:11], v[0:1], 2, s[10:11]
	v_mov_b32_e32 v1, 0
	v_mov_b32_e32 v0, 0
	s_and_saveexec_b64 s[8:9], vcc
	s_cbranch_execz .LBB0_114
	v_ashrrev_i32_e32 v13, 31, v12
	v_lshlrev_b64 v[2:3], 12, v[12:13]
	v_lshl_add_u64 v[2:3], v[10:11], 0, v[2:3]
	global_load_dword v0, v[2:3], off nt
.LBB0_114:
	s_or_b64 exec, exec, s[8:9]
	s_and_saveexec_b64 s[8:9], vcc
	s_cbranch_execz .LBB0_116
	v_add_u32_e32 v2, 8, v12
	v_ashrrev_i32_e32 v3, 31, v2
	v_lshlrev_b64 v[2:3], 12, v[2:3]
	v_lshl_add_u64 v[2:3], v[10:11], 0, v[2:3]
	global_load_dword v1, v[2:3], off nt
.LBB0_116:
	s_or_b64 exec, exec, s[8:9]
	v_mov_b32_e32 v3, 0
	v_mov_b32_e32 v2, 0
	s_and_saveexec_b64 s[8:9], vcc
	s_cbranch_execz .LBB0_118
	v_add_u32_e32 v4, 16, v12
	v_ashrrev_i32_e32 v5, 31, v4
	v_lshlrev_b64 v[4:5], 12, v[4:5]
	v_lshl_add_u64 v[4:5], v[10:11], 0, v[4:5]
	global_load_dword v2, v[4:5], off nt
.LBB0_118:
	s_or_b64 exec, exec, s[8:9]
	s_and_saveexec_b64 s[8:9], vcc
	s_cbranch_execz .LBB0_120
	v_add_u32_e32 v4, 24, v12
	v_ashrrev_i32_e32 v5, 31, v4
	v_lshlrev_b64 v[4:5], 12, v[4:5]
	v_lshl_add_u64 v[4:5], v[10:11], 0, v[4:5]
	global_load_dword v3, v[4:5], off nt
.LBB0_120:
	s_or_b64 exec, exec, s[8:9]
	v_mov_b32_e32 v5, 0
	v_mov_b32_e32 v4, 0
	s_and_saveexec_b64 s[8:9], vcc
	s_cbranch_execz .LBB0_122
	v_add_u32_e32 v6, 32, v12
	v_ashrrev_i32_e32 v7, 31, v6
	v_lshlrev_b64 v[6:7], 12, v[6:7]
	v_lshl_add_u64 v[6:7], v[10:11], 0, v[6:7]
	global_load_dword v4, v[6:7], off nt
.LBB0_122:
	s_or_b64 exec, exec, s[8:9]
	s_and_saveexec_b64 s[8:9], vcc
	s_cbranch_execz .LBB0_124
	v_add_u32_e32 v6, 40, v12
	v_ashrrev_i32_e32 v7, 31, v6
	v_lshlrev_b64 v[6:7], 12, v[6:7]
	v_lshl_add_u64 v[6:7], v[10:11], 0, v[6:7]
	global_load_dword v5, v[6:7], off nt
.LBB0_124:
	s_or_b64 exec, exec, s[8:9]
	v_mov_b32_e32 v7, 0
	v_mov_b32_e32 v6, 0
	s_and_saveexec_b64 s[8:9], vcc
	s_cbranch_execz .LBB0_126
	v_add_u32_e32 v20, 48, v12
	v_ashrrev_i32_e32 v21, 31, v20
	v_lshlrev_b64 v[20:21], 12, v[20:21]
	v_lshl_add_u64 v[20:21], v[10:11], 0, v[20:21]
	global_load_dword v6, v[20:21], off nt
.LBB0_126:
	s_or_b64 exec, exec, s[8:9]
	s_and_saveexec_b64 s[8:9], vcc
	s_cbranch_execz .LBB0_109
	v_add_u32_e32 v12, 56, v12
	v_ashrrev_i32_e32 v13, 31, v12
	v_lshlrev_b64 v[12:13], 12, v[12:13]
	v_lshl_add_u64 v[10:11], v[10:11], 0, v[12:13]
	global_load_dword v7, v[10:11], off nt
	s_branch .LBB0_109
.LBB0_128:
	s_lshl_b32 s0, s2, 3
	v_writelane_b32 v248, s0, 4
	s_lshl_b32 s58, s94, 3
	v_mbcnt_lo_u32_b32 v213, -1, 0
	s_mov_b32 s12, 0x800000
	s_movk_i32 s13, 0x49ff
	s_load_dwordx4 s[76:79], s[72:73], 0x0
	s_load_dwordx2 s[80:81], s[72:73], 0x10
	s_load_dwordx2 s[82:83], s[72:73], 0x40
	s_load_dwordx2 s[84:85], s[72:73], 0xb8
	v_lshrrev_b32_e32 v86, 6, v212
	v_and_b32_e32 v87, 63, v212
	s_nop 0
	v_readfirstlane_b32 s74, v86
	v_lshlrev_b32_e32 v84, 4, v87
	v_lshlrev_b32_e32 v85, 3, v87
	v_xor_b32_e32 v184, 32, v87
	v_xor_b32_e32 v185, 16, v87
	v_xor_b32_e32 v186, 8, v87
	v_xor_b32_e32 v187, 4, v87
	v_xor_b32_e32 v188, 2, v87
	v_xor_b32_e32 v189, 1, v87
	v_lshlrev_b32_e32 v184, 2, v184
	v_lshlrev_b32_e32 v185, 2, v185
	v_lshlrev_b32_e32 v186, 2, v186
	v_lshlrev_b32_e32 v187, 2, v187
	v_lshlrev_b32_e32 v188, 2, v188
	v_lshlrev_b32_e32 v189, 2, v189
	v_mov_b32_e32 v190, 0x358637bd
	s_add_u32 s66, s42, 0x2100000
	s_addc_u32 s67, s43, 0
	s_add_u32 s68, s42, 0x4200000
	s_addc_u32 s69, s43, 0
	s_add_i32 s74, s74, s0
	s_mov_b32 s75, s74
	s_waitcnt lgkmcnt(0)
	global_load_dwordx4 v[88:91], v84, s[82:83]
	global_load_dwordx4 v[92:95], v84, s[82:83] offset:1024
	global_load_dwordx4 v[96:99], v84, s[82:83] offset:2048
	global_load_dwordx4 v[100:103], v84, s[82:83] offset:3072
	global_load_dwordx4 v[104:107], v84, s[84:85]
	global_load_dwordx4 v[108:111], v84, s[84:85] offset:1024
	global_load_dwordx4 v[112:115], v84, s[84:85] offset:2048
	global_load_dwordx4 v[116:119], v84, s[84:85] offset:3072
	s_cmp_lt_u32 s75, 0x4000
	s_cselect_b32 s88, s76, s78
	s_cselect_b32 s89, s77, s79
	s_cselect_b32 s92, 0, 0x4000
	s_cmp_lt_u32 s75, 0x4200
	s_cselect_b32 s88, s88, s80
	s_cselect_b32 s89, s89, s81
	s_cselect_b32 s92, s92, 0x4200
	s_sub_u32 s92, s75, s92
	s_cmp_lt_u32 s75, 0x4a00
	s_cselect_b32 s92, s92, 0
	s_lshl_b32 s93, s92, 12
	s_add_u32 s88, s88, s93
	s_addc_u32 s89, s89, 0
	s_add_u32 s75, s75, s58
	global_load_dwordx4 v[120:123], v84, s[88:89] nt
	global_load_dwordx4 v[124:127], v84, s[88:89] offset:1024 nt
	global_load_dwordx4 v[128:131], v84, s[88:89] offset:2048 nt
	global_load_dwordx4 v[132:135], v84, s[88:89] offset:3072 nt
	s_cmp_lt_u32 s75, 0x4000
	s_cselect_b32 s88, s76, s78
	s_cselect_b32 s89, s77, s79
	s_cselect_b32 s92, 0, 0x4000
	s_cmp_lt_u32 s75, 0x4200
	s_cselect_b32 s88, s88, s80
	s_cselect_b32 s89, s89, s81
	s_cselect_b32 s92, s92, 0x4200
	s_sub_u32 s92, s75, s92
	s_cmp_lt_u32 s75, 0x4a00
	s_cselect_b32 s92, s92, 0
	s_lshl_b32 s93, s92, 12
	s_add_u32 s88, s88, s93
	s_addc_u32 s89, s89, 0
	s_add_u32 s75, s75, s58
	global_load_dwordx4 v[136:139], v84, s[88:89] nt
	global_load_dwordx4 v[140:143], v84, s[88:89] offset:1024 nt
	global_load_dwordx4 v[144:147], v84, s[88:89] offset:2048 nt
	global_load_dwordx4 v[148:151], v84, s[88:89] offset:3072 nt
	s_cmp_lt_u32 s75, 0x4000
	s_cselect_b32 s88, s76, s78
	s_cselect_b32 s89, s77, s79
	s_cselect_b32 s92, 0, 0x4000
	s_cmp_lt_u32 s75, 0x4200
	s_cselect_b32 s88, s88, s80
	s_cselect_b32 s89, s89, s81
	s_cselect_b32 s92, s92, 0x4200
	s_sub_u32 s92, s75, s92
	s_cmp_lt_u32 s75, 0x4a00
	s_cselect_b32 s92, s92, 0
	s_lshl_b32 s93, s92, 12
	s_add_u32 s88, s88, s93
	s_addc_u32 s89, s89, 0
	s_add_u32 s75, s75, s58
	global_load_dwordx4 v[152:155], v84, s[88:89] nt
	global_load_dwordx4 v[156:159], v84, s[88:89] offset:1024 nt
	global_load_dwordx4 v[160:163], v84, s[88:89] offset:2048 nt
	global_load_dwordx4 v[164:167], v84, s[88:89] offset:3072 nt
	s_cmp_lt_u32 s74, 0x4a00
	s_cbranch_scc0 .Lp0n_done
; DI u32x4 pk8(f32x4 a, f32x4 b) { u32x4 w; w.x = pk2(a[0], a[1]); w.y = pk2(a[2], a[3]); w.z = pk2(b[0], b[1]); w.w = pk2(b[2], b[3]); return w; }
; DI float wave_sum(float v) { for (int o = 32; o >= 1; o >>= 1) v += __shfl_xor(v, o); return v; }
; DI void rownorm_store(const f32x4 (&v)[4], const float* w, bf16_t* o, int lane) {
;   float ss = 0.f;
; #pragma unroll
;   for (int e = 0; e < 4; ++e) ss += v[e][0] * v[e][0] + v[e][1] * v[e][1] + v[e][2] * v[e][2] + v[e][3] * v[e][3];
;   ss = wave_sum(ss); const float rstd = rsqrtf(ss * (1.f / 1024.f) + EPS);
; #pragma unroll
;   for (int i = 0; i < 2; ++i) { const f32x4 w0 = *(const f32x4*)(w + RCOL(2 * i)), w1 = *(const f32x4*)(w + RCOL(2 * i + 1));
;     *(u32x4*)(o + i * 512 + lane * 8) = pk8(v[2 * i] * rstd * w0, v[2 * i + 1] * rstd * w1); }
; }
; DI void phase_prep(const Params& p, ldsp lds, int tid_) {
;     ...
;     for (int r = wv; r < NR; r += nwv) {
;       const int rn = r + 2 * nwv; f32x4 v2[4];
;       const int rc = rn < NR ? rn : r;
; #pragma unroll
;       for (int i = 0; i < 4; ++i) v2[i] = *(const f32x4*)(prep_row_src(p, rc) + RCOL(i));
;       if (r < T) rownorm_store(v0, p.in[8], (bf16_t*)(ws + B_XA) + (size_t)r * D, lane);
;       else rownorm_store(v0, p.in[23], (bf16_t*)(ws + B_MN) + (size_t)(r - T) * D, lane);
; #pragma unroll
;       for (int i = 0; i < 4; ++i) { v0[i] = v1[i]; v1[i] = v2[i]; }
	s_cmp_lt_u32 s75, 0x4000
	s_cselect_b32 s88, s76, s78
	s_cselect_b32 s89, s77, s79
	s_cselect_b32 s92, 0, 0x4000
	s_cmp_lt_u32 s75, 0x4200
	s_cselect_b32 s88, s88, s80
	s_cselect_b32 s89, s89, s81
	s_cselect_b32 s92, s92, 0x4200
	s_sub_u32 s92, s75, s92
	s_cmp_lt_u32 s75, 0x4a00
	s_cselect_b32 s92, s92, 0
	s_lshl_b32 s93, s92, 12
	s_add_u32 s88, s88, s93
	s_addc_u32 s89, s89, 0
	s_add_u32 s75, s75, s58
	global_load_dwordx4 v[168:171], v84, s[88:89] nt
	global_load_dwordx4 v[172:175], v84, s[88:89] offset:1024 nt
	global_load_dwordx4 v[176:179], v84, s[88:89] offset:2048 nt
	global_load_dwordx4 v[180:183], v84, s[88:89] offset:3072 nt
	s_waitcnt vmcnt(12)
	v_pk_mul_f32 v[192:193], v[120:121], v[120:121]
	v_pk_fma_f32 v[192:193], v[122:123], v[122:123], v[192:193]
	v_pk_fma_f32 v[192:193], v[124:125], v[124:125], v[192:193]
	v_pk_fma_f32 v[192:193], v[126:127], v[126:127], v[192:193]
	v_pk_fma_f32 v[192:193], v[128:129], v[128:129], v[192:193]
	v_pk_fma_f32 v[192:193], v[130:131], v[130:131], v[192:193]
	v_pk_fma_f32 v[192:193], v[132:133], v[132:133], v[192:193]
	v_pk_fma_f32 v[192:193], v[134:135], v[134:135], v[192:193]
	s_cmp_lt_u32 s74, 0x4200
	s_cselect_b32 s90, s66, s68
	s_cselect_b32 s91, s67, s69
	s_cselect_b32 s92, 0, 0x4200
	s_sub_u32 s92, s74, s92
	s_lshl_b32 s92, s92, 11
	s_add_u32 s90, s90, s92
	s_addc_u32 s91, s91, 0
	v_add_f32_e32 v194, v192, v193
	ds_bpermute_b32 v195, v184, v194
	s_waitcnt lgkmcnt(0)
	v_add_f32_e32 v194, v194, v195
	ds_bpermute_b32 v195, v185, v194
	s_waitcnt lgkmcnt(0)
	v_add_f32_e32 v194, v194, v195
	ds_bpermute_b32 v195, v186, v194
	s_waitcnt lgkmcnt(0)
	v_add_f32_e32 v194, v194, v195
	ds_bpermute_b32 v195, v187, v194
	s_waitcnt lgkmcnt(0)
	v_add_f32_e32 v194, v194, v195
	ds_bpermute_b32 v195, v188, v194
	s_waitcnt lgkmcnt(0)
	v_add_f32_e32 v194, v194, v195
	ds_bpermute_b32 v195, v189, v194
	s_waitcnt lgkmcnt(0)
	v_add_f32_e32 v194, v194, v195
	v_fmamk_f32 v196, v194, 0x3a800000, v190
	v_mul_f32_e32 v197, 0x4b800000, v196
	v_cmp_gt_f32_e32 vcc, s12, v196
	s_nop 1
	v_cndmask_b32_e32 v196, v196, v197, vcc
	v_rsq_f32_e32 v197, v196
	s_nop 0
	v_mul_f32_e32 v196, 0x45800000, v197
	v_cndmask_b32_e32 v198, v197, v196, vcc
	v_pk_mul_f32 v[120:121], v[120:121], v[198:199] op_sel_hi:[1,0]
	v_pk_mul_f32 v[122:123], v[122:123], v[198:199] op_sel_hi:[1,0]
	v_pk_mul_f32 v[124:125], v[124:125], v[198:199] op_sel_hi:[1,0]
	v_pk_mul_f32 v[126:127], v[126:127], v[198:199] op_sel_hi:[1,0]
	v_pk_mul_f32 v[128:129], v[128:129], v[198:199] op_sel_hi:[1,0]
	v_pk_mul_f32 v[130:131], v[130:131], v[198:199] op_sel_hi:[1,0]
	v_pk_mul_f32 v[132:133], v[132:133], v[198:199] op_sel_hi:[1,0]
	v_pk_mul_f32 v[134:135], v[134:135], v[198:199] op_sel_hi:[1,0]
	s_cmp_lt_u32 s74, 0x4200
	s_cbranch_scc0 .Lp0n_wb_q0
	v_pk_mul_f32 v[120:121], v[88:89], v[120:121]
	v_pk_mul_f32 v[122:123], v[90:91], v[122:123]
	v_pk_mul_f32 v[124:125], v[92:93], v[124:125]
	v_pk_mul_f32 v[126:127], v[94:95], v[126:127]
	v_pk_mul_f32 v[128:129], v[96:97], v[128:129]
	v_pk_mul_f32 v[130:131], v[98:99], v[130:131]
	v_pk_mul_f32 v[132:133], v[100:101], v[132:133]
	v_pk_mul_f32 v[134:135], v[102:103], v[134:135]
	s_branch .Lp0n_wd_q0
.Lp0n_wb_q0:
	v_pk_mul_f32 v[120:121], v[104:105], v[120:121]
	v_pk_mul_f32 v[122:123], v[106:107], v[122:123]
	v_pk_mul_f32 v[124:125], v[108:109], v[124:125]
	v_pk_mul_f32 v[126:127], v[110:111], v[126:127]
	v_pk_mul_f32 v[128:129], v[112:113], v[128:129]
	v_pk_mul_f32 v[130:131], v[114:115], v[130:131]
	v_pk_mul_f32 v[132:133], v[116:117], v[132:133]
	v_pk_mul_f32 v[134:135], v[118:119], v[134:135]
.Lp0n_wd_q0:
	v_cvt_pk_bf16_f32 v200, v120, v121
	v_cvt_pk_bf16_f32 v201, v122, v123
	v_cvt_pk_bf16_f32 v202, v124, v125
	v_cvt_pk_bf16_f32 v203, v126, v127
	v_cvt_pk_bf16_f32 v204, v128, v129
	v_cvt_pk_bf16_f32 v205, v130, v131
	v_cvt_pk_bf16_f32 v206, v132, v133
	v_cvt_pk_bf16_f32 v207, v134, v135
	global_store_dwordx2 v85, v[200:201], s[90:91]
	global_store_dwordx2 v85, v[202:203], s[90:91] offset:512
	global_store_dwordx2 v85, v[204:205], s[90:91] offset:1024
	global_store_dwordx2 v85, v[206:207], s[90:91] offset:1536
	s_add_u32 s74, s74, s58
	s_cmp_lt_u32 s74, 0x4a00
	s_cbranch_scc0 .Lp0n_done
	s_cmp_lt_u32 s75, 0x4000
	s_cselect_b32 s88, s76, s78
	s_cselect_b32 s89, s77, s79
	s_cselect_b32 s92, 0, 0x4000
	s_cmp_lt_u32 s75, 0x4200
	s_cselect_b32 s88, s88, s80
	s_cselect_b32 s89, s89, s81
	s_cselect_b32 s92, s92, 0x4200
	s_sub_u32 s92, s75, s92
	s_cmp_lt_u32 s75, 0x4a00
	s_cselect_b32 s92, s92, 0
	s_lshl_b32 s93, s92, 12
	s_add_u32 s88, s88, s93
	s_addc_u32 s89, s89, 0
	s_add_u32 s75, s75, s58
	global_load_dwordx4 v[120:123], v84, s[88:89] nt
	global_load_dwordx4 v[124:127], v84, s[88:89] offset:1024 nt
	global_load_dwordx4 v[128:131], v84, s[88:89] offset:2048 nt
	global_load_dwordx4 v[132:135], v84, s[88:89] offset:3072 nt
	s_waitcnt vmcnt(16)
	v_pk_mul_f32 v[192:193], v[136:137], v[136:137]
	v_pk_fma_f32 v[192:193], v[138:139], v[138:139], v[192:193]
	v_pk_fma_f32 v[192:193], v[140:141], v[140:141], v[192:193]
	v_pk_fma_f32 v[192:193], v[142:143], v[142:143], v[192:193]
	v_pk_fma_f32 v[192:193], v[144:145], v[144:145], v[192:193]
	v_pk_fma_f32 v[192:193], v[146:147], v[146:147], v[192:193]
	v_pk_fma_f32 v[192:193], v[148:149], v[148:149], v[192:193]
	v_pk_fma_f32 v[192:193], v[150:151], v[150:151], v[192:193]
	s_cmp_lt_u32 s74, 0x4200
	s_cselect_b32 s90, s66, s68
	s_cselect_b32 s91, s67, s69
	s_cselect_b32 s92, 0, 0x4200
	s_sub_u32 s92, s74, s92
	s_lshl_b32 s92, s92, 11
	s_add_u32 s90, s90, s92
	s_addc_u32 s91, s91, 0
	v_add_f32_e32 v194, v192, v193
	ds_bpermute_b32 v195, v184, v194
	s_waitcnt lgkmcnt(0)
	v_add_f32_e32 v194, v194, v195
	ds_bpermute_b32 v195, v185, v194
	s_waitcnt lgkmcnt(0)
	v_add_f32_e32 v194, v194, v195
	ds_bpermute_b32 v195, v186, v194
	s_waitcnt lgkmcnt(0)
	v_add_f32_e32 v194, v194, v195
	ds_bpermute_b32 v195, v187, v194
	s_waitcnt lgkmcnt(0)
	v_add_f32_e32 v194, v194, v195
	ds_bpermute_b32 v195, v188, v194
	s_waitcnt lgkmcnt(0)
	v_add_f32_e32 v194, v194, v195
	ds_bpermute_b32 v195, v189, v194
	s_waitcnt lgkmcnt(0)
	v_add_f32_e32 v194, v194, v195
	v_fmamk_f32 v196, v194, 0x3a800000, v190
	v_mul_f32_e32 v197, 0x4b800000, v196
	v_cmp_gt_f32_e32 vcc, s12, v196
	s_nop 1
	v_cndmask_b32_e32 v196, v196, v197, vcc
	v_rsq_f32_e32 v197, v196
	s_nop 0
	v_mul_f32_e32 v196, 0x45800000, v197
	v_cndmask_b32_e32 v198, v197, v196, vcc
	v_pk_mul_f32 v[136:137], v[136:137], v[198:199] op_sel_hi:[1,0]
	v_pk_mul_f32 v[138:139], v[138:139], v[198:199] op_sel_hi:[1,0]
	v_pk_mul_f32 v[140:141], v[140:141], v[198:199] op_sel_hi:[1,0]
	v_pk_mul_f32 v[142:143], v[142:143], v[198:199] op_sel_hi:[1,0]
	v_pk_mul_f32 v[144:145], v[144:145], v[198:199] op_sel_hi:[1,0]
	v_pk_mul_f32 v[146:147], v[146:147], v[198:199] op_sel_hi:[1,0]
	v_pk_mul_f32 v[148:149], v[148:149], v[198:199] op_sel_hi:[1,0]
	v_pk_mul_f32 v[150:151], v[150:151], v[198:199] op_sel_hi:[1,0]
	s_cmp_lt_u32 s74, 0x4200
	s_cbranch_scc0 .Lp0n_wb_q1
; DI u32x4 pk8(f32x4 a, f32x4 b) { u32x4 w; w.x = pk2(a[0], a[1]); w.y = pk2(a[2], a[3]); w.z = pk2(b[0], b[1]); w.w = pk2(b[2], b[3]); return w; }
; DI float wave_sum(float v) { for (int o = 32; o >= 1; o >>= 1) v += __shfl_xor(v, o); return v; }
; DI void rownorm_store(const f32x4 (&v)[4], const float* w, bf16_t* o, int lane) {
;   float ss = 0.f;
; #pragma unroll
;   for (int e = 0; e < 4; ++e) ss += v[e][0] * v[e][0] + v[e][1] * v[e][1] + v[e][2] * v[e][2] + v[e][3] * v[e][3];
;   ss = wave_sum(ss); const float rstd = rsqrtf(ss * (1.f / 1024.f) + EPS);
; #pragma unroll
;   for (int i = 0; i < 2; ++i) { const f32x4 w0 = *(const f32x4*)(w + RCOL(2 * i)), w1 = *(const f32x4*)(w + RCOL(2 * i + 1));
;     *(u32x4*)(o + i * 512 + lane * 8) = pk8(v[2 * i] * rstd * w0, v[2 * i + 1] * rstd * w1); }
; }
; DI void phase_prep(const Params& p, ldsp lds, int tid_) {
;     ...
;     for (int r = wv; r < NR; r += nwv) {
;       const int rn = r + 2 * nwv; f32x4 v2[4];
;       const int rc = rn < NR ? rn : r;
; #pragma unroll
;       for (int i = 0; i < 4; ++i) v2[i] = *(const f32x4*)(prep_row_src(p, rc) + RCOL(i));
;       if (r < T) rownorm_store(v0, p.in[8], (bf16_t*)(ws + B_XA) + (size_t)r * D, lane);
;       else rownorm_store(v0, p.in[23], (bf16_t*)(ws + B_MN) + (size_t)(r - T) * D, lane);
; #pragma unroll
;       for (int i = 0; i < 4; ++i) { v0[i] = v1[i]; v1[i] = v2[i]; }
	v_pk_mul_f32 v[136:137], v[88:89], v[136:137]
	v_pk_mul_f32 v[138:139], v[90:91], v[138:139]
	v_pk_mul_f32 v[140:141], v[92:93], v[140:141]
	v_pk_mul_f32 v[142:143], v[94:95], v[142:143]
	v_pk_mul_f32 v[144:145], v[96:97], v[144:145]
	v_pk_mul_f32 v[146:147], v[98:99], v[146:147]
	v_pk_mul_f32 v[148:149], v[100:101], v[148:149]
	v_pk_mul_f32 v[150:151], v[102:103], v[150:151]
	s_branch .Lp0n_wd_q1
.Lp0n_wb_q1:
	v_pk_mul_f32 v[136:137], v[104:105], v[136:137]
	v_pk_mul_f32 v[138:139], v[106:107], v[138:139]
	v_pk_mul_f32 v[140:141], v[108:109], v[140:141]
	v_pk_mul_f32 v[142:143], v[110:111], v[142:143]
	v_pk_mul_f32 v[144:145], v[112:113], v[144:145]
	v_pk_mul_f32 v[146:147], v[114:115], v[146:147]
	v_pk_mul_f32 v[148:149], v[116:117], v[148:149]
	v_pk_mul_f32 v[150:151], v[118:119], v[150:151]
.Lp0n_wd_q1:
	v_cvt_pk_bf16_f32 v200, v136, v137
	v_cvt_pk_bf16_f32 v201, v138, v139
	v_cvt_pk_bf16_f32 v202, v140, v141
	v_cvt_pk_bf16_f32 v203, v142, v143
	v_cvt_pk_bf16_f32 v204, v144, v145
	v_cvt_pk_bf16_f32 v205, v146, v147
	v_cvt_pk_bf16_f32 v206, v148, v149
	v_cvt_pk_bf16_f32 v207, v150, v151
	global_store_dwordx2 v85, v[200:201], s[90:91]
	global_store_dwordx2 v85, v[202:203], s[90:91] offset:512
	global_store_dwordx2 v85, v[204:205], s[90:91] offset:1024
	global_store_dwordx2 v85, v[206:207], s[90:91] offset:1536
	s_add_u32 s74, s74, s58
	s_cmp_lt_u32 s74, 0x4a00
	s_cbranch_scc0 .Lp0n_done
	s_cmp_lt_u32 s75, 0x4000
	s_cselect_b32 s88, s76, s78
	s_cselect_b32 s89, s77, s79
	s_cselect_b32 s92, 0, 0x4000
	s_cmp_lt_u32 s75, 0x4200
	s_cselect_b32 s88, s88, s80
	s_cselect_b32 s89, s89, s81
	s_cselect_b32 s92, s92, 0x4200
	s_sub_u32 s92, s75, s92
	s_cmp_lt_u32 s75, 0x4a00
	s_cselect_b32 s92, s92, 0
	s_lshl_b32 s93, s92, 12
	s_add_u32 s88, s88, s93
	s_addc_u32 s89, s89, 0
	s_add_u32 s75, s75, s58
	global_load_dwordx4 v[136:139], v84, s[88:89] nt
	global_load_dwordx4 v[140:143], v84, s[88:89] offset:1024 nt
	global_load_dwordx4 v[144:147], v84, s[88:89] offset:2048 nt
	global_load_dwordx4 v[148:151], v84, s[88:89] offset:3072 nt
	s_waitcnt vmcnt(20)
	v_pk_mul_f32 v[192:193], v[152:153], v[152:153]
	v_pk_fma_f32 v[192:193], v[154:155], v[154:155], v[192:193]
	v_pk_fma_f32 v[192:193], v[156:157], v[156:157], v[192:193]
	v_pk_fma_f32 v[192:193], v[158:159], v[158:159], v[192:193]
	v_pk_fma_f32 v[192:193], v[160:161], v[160:161], v[192:193]
	v_pk_fma_f32 v[192:193], v[162:163], v[162:163], v[192:193]
	v_pk_fma_f32 v[192:193], v[164:165], v[164:165], v[192:193]
	v_pk_fma_f32 v[192:193], v[166:167], v[166:167], v[192:193]
	s_cmp_lt_u32 s74, 0x4200
	s_cselect_b32 s90, s66, s68
	s_cselect_b32 s91, s67, s69
	s_cselect_b32 s92, 0, 0x4200
	s_sub_u32 s92, s74, s92
	s_lshl_b32 s92, s92, 11
	s_add_u32 s90, s90, s92
	s_addc_u32 s91, s91, 0
	v_add_f32_e32 v194, v192, v193
	ds_bpermute_b32 v195, v184, v194
	s_waitcnt lgkmcnt(0)
	v_add_f32_e32 v194, v194, v195
	ds_bpermute_b32 v195, v185, v194
	s_waitcnt lgkmcnt(0)
	v_add_f32_e32 v194, v194, v195
	ds_bpermute_b32 v195, v186, v194
	s_waitcnt lgkmcnt(0)
	v_add_f32_e32 v194, v194, v195
	ds_bpermute_b32 v195, v187, v194
	s_waitcnt lgkmcnt(0)
	v_add_f32_e32 v194, v194, v195
	ds_bpermute_b32 v195, v188, v194
	s_waitcnt lgkmcnt(0)
	v_add_f32_e32 v194, v194, v195
	ds_bpermute_b32 v195, v189, v194
	s_waitcnt lgkmcnt(0)
	v_add_f32_e32 v194, v194, v195
	v_fmamk_f32 v196, v194, 0x3a800000, v190
	v_mul_f32_e32 v197, 0x4b800000, v196
	v_cmp_gt_f32_e32 vcc, s12, v196
	s_nop 1
	v_cndmask_b32_e32 v196, v196, v197, vcc
	v_rsq_f32_e32 v197, v196
	s_nop 0
	v_mul_f32_e32 v196, 0x45800000, v197
	v_cndmask_b32_e32 v198, v197, v196, vcc
	v_pk_mul_f32 v[152:153], v[152:153], v[198:199] op_sel_hi:[1,0]
	v_pk_mul_f32 v[154:155], v[154:155], v[198:199] op_sel_hi:[1,0]
	v_pk_mul_f32 v[156:157], v[156:157], v[198:199] op_sel_hi:[1,0]
	v_pk_mul_f32 v[158:159], v[158:159], v[198:199] op_sel_hi:[1,0]
	v_pk_mul_f32 v[160:161], v[160:161], v[198:199] op_sel_hi:[1,0]
	v_pk_mul_f32 v[162:163], v[162:163], v[198:199] op_sel_hi:[1,0]
	v_pk_mul_f32 v[164:165], v[164:165], v[198:199] op_sel_hi:[1,0]
	v_pk_mul_f32 v[166:167], v[166:167], v[198:199] op_sel_hi:[1,0]
	s_cmp_lt_u32 s74, 0x4200
	s_cbranch_scc0 .Lp0n_wb_q2
	v_pk_mul_f32 v[152:153], v[88:89], v[152:153]
	v_pk_mul_f32 v[154:155], v[90:91], v[154:155]
	v_pk_mul_f32 v[156:157], v[92:93], v[156:157]
	v_pk_mul_f32 v[158:159], v[94:95], v[158:159]
	v_pk_mul_f32 v[160:161], v[96:97], v[160:161]
	v_pk_mul_f32 v[162:163], v[98:99], v[162:163]
	v_pk_mul_f32 v[164:165], v[100:101], v[164:165]
	v_pk_mul_f32 v[166:167], v[102:103], v[166:167]
	s_branch .Lp0n_wd_q2
.Lp0n_wb_q2:
	v_pk_mul_f32 v[152:153], v[104:105], v[152:153]
	v_pk_mul_f32 v[154:155], v[106:107], v[154:155]
	v_pk_mul_f32 v[156:157], v[108:109], v[156:157]
	v_pk_mul_f32 v[158:159], v[110:111], v[158:159]
	v_pk_mul_f32 v[160:161], v[112:113], v[160:161]
	v_pk_mul_f32 v[162:163], v[114:115], v[162:163]
	v_pk_mul_f32 v[164:165], v[116:117], v[164:165]
	v_pk_mul_f32 v[166:167], v[118:119], v[166:167]
.Lp0n_wd_q2:
	v_cvt_pk_bf16_f32 v200, v152, v153
	v_cvt_pk_bf16_f32 v201, v154, v155
	v_cvt_pk_bf16_f32 v202, v156, v157
	v_cvt_pk_bf16_f32 v203, v158, v159
	v_cvt_pk_bf16_f32 v204, v160, v161
	v_cvt_pk_bf16_f32 v205, v162, v163
	v_cvt_pk_bf16_f32 v206, v164, v165
	v_cvt_pk_bf16_f32 v207, v166, v167
	global_store_dwordx2 v85, v[200:201], s[90:91]
	global_store_dwordx2 v85, v[202:203], s[90:91] offset:512
	global_store_dwordx2 v85, v[204:205], s[90:91] offset:1024
	global_store_dwordx2 v85, v[206:207], s[90:91] offset:1536
	s_add_u32 s74, s74, s58
; DI u32x4 pk8(f32x4 a, f32x4 b) { u32x4 w; w.x = pk2(a[0], a[1]); w.y = pk2(a[2], a[3]); w.z = pk2(b[0], b[1]); w.w = pk2(b[2], b[3]); return w; }
; DI float wave_sum(float v) { for (int o = 32; o >= 1; o >>= 1) v += __shfl_xor(v, o); return v; }
; DI void rownorm_store(const f32x4 (&v)[4], const float* w, bf16_t* o, int lane) {
;   float ss = 0.f;
; #pragma unroll
;   for (int e = 0; e < 4; ++e) ss += v[e][0] * v[e][0] + v[e][1] * v[e][1] + v[e][2] * v[e][2] + v[e][3] * v[e][3];
;   ss = wave_sum(ss); const float rstd = rsqrtf(ss * (1.f / 1024.f) + EPS);
; #pragma unroll
;   for (int i = 0; i < 2; ++i) { const f32x4 w0 = *(const f32x4*)(w + RCOL(2 * i)), w1 = *(const f32x4*)(w + RCOL(2 * i + 1));
;     *(u32x4*)(o + i * 512 + lane * 8) = pk8(v[2 * i] * rstd * w0, v[2 * i + 1] * rstd * w1); }
; }
; DI void phase_prep(const Params& p, ldsp lds, int tid_) {
;     ...
;     for (int r = wv; r < NR; r += nwv) {
;       const int rn = r + 2 * nwv; f32x4 v2[4];
;       const int rc = rn < NR ? rn : r;
; #pragma unroll
;       for (int i = 0; i < 4; ++i) v2[i] = *(const f32x4*)(prep_row_src(p, rc) + RCOL(i));
;       if (r < T) rownorm_store(v0, p.in[8], (bf16_t*)(ws + B_XA) + (size_t)r * D, lane);
;       else rownorm_store(v0, p.in[23], (bf16_t*)(ws + B_MN) + (size_t)(r - T) * D, lane);
; #pragma unroll
;       for (int i = 0; i < 4; ++i) { v0[i] = v1[i]; v1[i] = v2[i]; }
.Lp0n_loop:
	s_cmp_lt_u32 s74, 0x4a00
	s_cbranch_scc0 .Lp0n_done
	s_cmp_lt_u32 s75, 0x4000
	s_cselect_b32 s88, s76, s78
	s_cselect_b32 s89, s77, s79
	s_cselect_b32 s92, 0, 0x4000
	s_cmp_lt_u32 s75, 0x4200
	s_cselect_b32 s88, s88, s80
	s_cselect_b32 s89, s89, s81
	s_cselect_b32 s92, s92, 0x4200
	s_sub_u32 s92, s75, s92
	s_cmp_lt_u32 s75, 0x4a00
	s_cselect_b32 s92, s92, 0
	s_lshl_b32 s93, s92, 12
	s_add_u32 s88, s88, s93
	s_addc_u32 s89, s89, 0
	s_add_u32 s75, s75, s58
	global_load_dwordx4 v[152:155], v84, s[88:89] nt
	global_load_dwordx4 v[156:159], v84, s[88:89] offset:1024 nt
	global_load_dwordx4 v[160:163], v84, s[88:89] offset:2048 nt
	global_load_dwordx4 v[164:167], v84, s[88:89] offset:3072 nt
	s_waitcnt vmcnt(24)
	v_pk_mul_f32 v[192:193], v[168:169], v[168:169]
	v_pk_fma_f32 v[192:193], v[170:171], v[170:171], v[192:193]
	v_pk_fma_f32 v[192:193], v[172:173], v[172:173], v[192:193]
	v_pk_fma_f32 v[192:193], v[174:175], v[174:175], v[192:193]
	v_pk_fma_f32 v[192:193], v[176:177], v[176:177], v[192:193]
	v_pk_fma_f32 v[192:193], v[178:179], v[178:179], v[192:193]
	v_pk_fma_f32 v[192:193], v[180:181], v[180:181], v[192:193]
	v_pk_fma_f32 v[192:193], v[182:183], v[182:183], v[192:193]
	s_cmp_lt_u32 s74, 0x4200
	s_cselect_b32 s90, s66, s68
	s_cselect_b32 s91, s67, s69
	s_cselect_b32 s92, 0, 0x4200
	s_sub_u32 s92, s74, s92
	s_lshl_b32 s92, s92, 11
	s_add_u32 s90, s90, s92
	s_addc_u32 s91, s91, 0
	v_add_f32_e32 v194, v192, v193
	ds_bpermute_b32 v195, v184, v194
	s_waitcnt lgkmcnt(0)
	v_add_f32_e32 v194, v194, v195
	ds_bpermute_b32 v195, v185, v194
	s_waitcnt lgkmcnt(0)
	v_add_f32_e32 v194, v194, v195
	ds_bpermute_b32 v195, v186, v194
	s_waitcnt lgkmcnt(0)
	v_add_f32_e32 v194, v194, v195
	ds_bpermute_b32 v195, v187, v194
	s_waitcnt lgkmcnt(0)
	v_add_f32_e32 v194, v194, v195
	ds_bpermute_b32 v195, v188, v194
	s_waitcnt lgkmcnt(0)
	v_add_f32_e32 v194, v194, v195
	ds_bpermute_b32 v195, v189, v194
	s_waitcnt lgkmcnt(0)
	v_add_f32_e32 v194, v194, v195
	v_fmamk_f32 v196, v194, 0x3a800000, v190
	v_mul_f32_e32 v197, 0x4b800000, v196
	v_cmp_gt_f32_e32 vcc, s12, v196
	s_nop 1
	v_cndmask_b32_e32 v196, v196, v197, vcc
	v_rsq_f32_e32 v197, v196
	s_nop 0
	v_mul_f32_e32 v196, 0x45800000, v197
	v_cndmask_b32_e32 v198, v197, v196, vcc
	v_pk_mul_f32 v[168:169], v[168:169], v[198:199] op_sel_hi:[1,0]
	v_pk_mul_f32 v[170:171], v[170:171], v[198:199] op_sel_hi:[1,0]
	v_pk_mul_f32 v[172:173], v[172:173], v[198:199] op_sel_hi:[1,0]
	v_pk_mul_f32 v[174:175], v[174:175], v[198:199] op_sel_hi:[1,0]
	v_pk_mul_f32 v[176:177], v[176:177], v[198:199] op_sel_hi:[1,0]
	v_pk_mul_f32 v[178:179], v[178:179], v[198:199] op_sel_hi:[1,0]
	v_pk_mul_f32 v[180:181], v[180:181], v[198:199] op_sel_hi:[1,0]
	v_pk_mul_f32 v[182:183], v[182:183], v[198:199] op_sel_hi:[1,0]
	s_cmp_lt_u32 s74, 0x4200
	s_cbranch_scc0 .Lp0n_wb_l3
	v_pk_mul_f32 v[168:169], v[88:89], v[168:169]
	v_pk_mul_f32 v[170:171], v[90:91], v[170:171]
	v_pk_mul_f32 v[172:173], v[92:93], v[172:173]
	v_pk_mul_f32 v[174:175], v[94:95], v[174:175]
	v_pk_mul_f32 v[176:177], v[96:97], v[176:177]
	v_pk_mul_f32 v[178:179], v[98:99], v[178:179]
	v_pk_mul_f32 v[180:181], v[100:101], v[180:181]
	v_pk_mul_f32 v[182:183], v[102:103], v[182:183]
	s_branch .Lp0n_wd_l3
.Lp0n_wb_l3:
	v_pk_mul_f32 v[168:169], v[104:105], v[168:169]
	v_pk_mul_f32 v[170:171], v[106:107], v[170:171]
	v_pk_mul_f32 v[172:173], v[108:109], v[172:173]
	v_pk_mul_f32 v[174:175], v[110:111], v[174:175]
	v_pk_mul_f32 v[176:177], v[112:113], v[176:177]
	v_pk_mul_f32 v[178:179], v[114:115], v[178:179]
	v_pk_mul_f32 v[180:181], v[116:117], v[180:181]
	v_pk_mul_f32 v[182:183], v[118:119], v[182:183]
; DI u32x4 pk8(f32x4 a, f32x4 b) { u32x4 w; w.x = pk2(a[0], a[1]); w.y = pk2(a[2], a[3]); w.z = pk2(b[0], b[1]); w.w = pk2(b[2], b[3]); return w; }
; DI float wave_sum(float v) { for (int o = 32; o >= 1; o >>= 1) v += __shfl_xor(v, o); return v; }
; DI void rownorm_store(const f32x4 (&v)[4], const float* w, bf16_t* o, int lane) {
;   float ss = 0.f;
; #pragma unroll
;   for (int e = 0; e < 4; ++e) ss += v[e][0] * v[e][0] + v[e][1] * v[e][1] + v[e][2] * v[e][2] + v[e][3] * v[e][3];
;   ss = wave_sum(ss); const float rstd = rsqrtf(ss * (1.f / 1024.f) + EPS);
; #pragma unroll
;   for (int i = 0; i < 2; ++i) { const f32x4 w0 = *(const f32x4*)(w + RCOL(2 * i)), w1 = *(const f32x4*)(w + RCOL(2 * i + 1));
;     *(u32x4*)(o + i * 512 + lane * 8) = pk8(v[2 * i] * rstd * w0, v[2 * i + 1] * rstd * w1); }
; }
; DI void phase_prep(const Params& p, ldsp lds, int tid_) {
;     ...
;     for (int r = wv; r < NR; r += nwv) {
;       const int rn = r + 2 * nwv; f32x4 v2[4];
;       const int rc = rn < NR ? rn : r;
; #pragma unroll
;       for (int i = 0; i < 4; ++i) v2[i] = *(const f32x4*)(prep_row_src(p, rc) + RCOL(i));
;       if (r < T) rownorm_store(v0, p.in[8], (bf16_t*)(ws + B_XA) + (size_t)r * D, lane);
;       else rownorm_store(v0, p.in[23], (bf16_t*)(ws + B_MN) + (size_t)(r - T) * D, lane);
; #pragma unroll
;       for (int i = 0; i < 4; ++i) { v0[i] = v1[i]; v1[i] = v2[i]; }
.Lp0n_wd_l3:
	v_cvt_pk_bf16_f32 v200, v168, v169
	v_cvt_pk_bf16_f32 v201, v170, v171
	v_cvt_pk_bf16_f32 v202, v172, v173
	v_cvt_pk_bf16_f32 v203, v174, v175
	v_cvt_pk_bf16_f32 v204, v176, v177
	v_cvt_pk_bf16_f32 v205, v178, v179
	v_cvt_pk_bf16_f32 v206, v180, v181
	v_cvt_pk_bf16_f32 v207, v182, v183
	global_store_dwordx2 v85, v[200:201], s[90:91]
	global_store_dwordx2 v85, v[202:203], s[90:91] offset:512
	global_store_dwordx2 v85, v[204:205], s[90:91] offset:1024
	global_store_dwordx2 v85, v[206:207], s[90:91] offset:1536
	s_add_u32 s74, s74, s58
	s_cmp_lt_u32 s74, 0x4a00
	s_cbranch_scc0 .Lp0n_done
	s_cmp_lt_u32 s75, 0x4000
	s_cselect_b32 s88, s76, s78
	s_cselect_b32 s89, s77, s79
	s_cselect_b32 s92, 0, 0x4000
	s_cmp_lt_u32 s75, 0x4200
	s_cselect_b32 s88, s88, s80
	s_cselect_b32 s89, s89, s81
	s_cselect_b32 s92, s92, 0x4200
	s_sub_u32 s92, s75, s92
	s_cmp_lt_u32 s75, 0x4a00
	s_cselect_b32 s92, s92, 0
	s_lshl_b32 s93, s92, 12
	s_add_u32 s88, s88, s93
	s_addc_u32 s89, s89, 0
	s_add_u32 s75, s75, s58
	global_load_dwordx4 v[168:171], v84, s[88:89] nt
	global_load_dwordx4 v[172:175], v84, s[88:89] offset:1024 nt
	global_load_dwordx4 v[176:179], v84, s[88:89] offset:2048 nt
	global_load_dwordx4 v[180:183], v84, s[88:89] offset:3072 nt
	s_waitcnt vmcnt(24)
	v_pk_mul_f32 v[192:193], v[120:121], v[120:121]
	v_pk_fma_f32 v[192:193], v[122:123], v[122:123], v[192:193]
	v_pk_fma_f32 v[192:193], v[124:125], v[124:125], v[192:193]
	v_pk_fma_f32 v[192:193], v[126:127], v[126:127], v[192:193]
	v_pk_fma_f32 v[192:193], v[128:129], v[128:129], v[192:193]
	v_pk_fma_f32 v[192:193], v[130:131], v[130:131], v[192:193]
	v_pk_fma_f32 v[192:193], v[132:133], v[132:133], v[192:193]
	v_pk_fma_f32 v[192:193], v[134:135], v[134:135], v[192:193]
	s_cmp_lt_u32 s74, 0x4200
	s_cselect_b32 s90, s66, s68
	s_cselect_b32 s91, s67, s69
	s_cselect_b32 s92, 0, 0x4200
	s_sub_u32 s92, s74, s92
	s_lshl_b32 s92, s92, 11
	s_add_u32 s90, s90, s92
	s_addc_u32 s91, s91, 0
	v_add_f32_e32 v194, v192, v193
	ds_bpermute_b32 v195, v184, v194
	s_waitcnt lgkmcnt(0)
	v_add_f32_e32 v194, v194, v195
	ds_bpermute_b32 v195, v185, v194
	s_waitcnt lgkmcnt(0)
	v_add_f32_e32 v194, v194, v195
	ds_bpermute_b32 v195, v186, v194
	s_waitcnt lgkmcnt(0)
	v_add_f32_e32 v194, v194, v195
	ds_bpermute_b32 v195, v187, v194
	s_waitcnt lgkmcnt(0)
	v_add_f32_e32 v194, v194, v195
	ds_bpermute_b32 v195, v188, v194
	s_waitcnt lgkmcnt(0)
	v_add_f32_e32 v194, v194, v195
	ds_bpermute_b32 v195, v189, v194
	s_waitcnt lgkmcnt(0)
	v_add_f32_e32 v194, v194, v195
	v_fmamk_f32 v196, v194, 0x3a800000, v190
	v_mul_f32_e32 v197, 0x4b800000, v196
	v_cmp_gt_f32_e32 vcc, s12, v196
	s_nop 1
	v_cndmask_b32_e32 v196, v196, v197, vcc
	v_rsq_f32_e32 v197, v196
	s_nop 0
	v_mul_f32_e32 v196, 0x45800000, v197
	v_cndmask_b32_e32 v198, v197, v196, vcc
	v_pk_mul_f32 v[120:121], v[120:121], v[198:199] op_sel_hi:[1,0]
	v_pk_mul_f32 v[122:123], v[122:123], v[198:199] op_sel_hi:[1,0]
	v_pk_mul_f32 v[124:125], v[124:125], v[198:199] op_sel_hi:[1,0]
	v_pk_mul_f32 v[126:127], v[126:127], v[198:199] op_sel_hi:[1,0]
	v_pk_mul_f32 v[128:129], v[128:129], v[198:199] op_sel_hi:[1,0]
	v_pk_mul_f32 v[130:131], v[130:131], v[198:199] op_sel_hi:[1,0]
	v_pk_mul_f32 v[132:133], v[132:133], v[198:199] op_sel_hi:[1,0]
	v_pk_mul_f32 v[134:135], v[134:135], v[198:199] op_sel_hi:[1,0]
	s_cmp_lt_u32 s74, 0x4200
	s_cbranch_scc0 .Lp0n_wb_l4
	v_pk_mul_f32 v[120:121], v[88:89], v[120:121]
	v_pk_mul_f32 v[122:123], v[90:91], v[122:123]
	v_pk_mul_f32 v[124:125], v[92:93], v[124:125]
	v_pk_mul_f32 v[126:127], v[94:95], v[126:127]
	v_pk_mul_f32 v[128:129], v[96:97], v[128:129]
	v_pk_mul_f32 v[130:131], v[98:99], v[130:131]
	v_pk_mul_f32 v[132:133], v[100:101], v[132:133]
	v_pk_mul_f32 v[134:135], v[102:103], v[134:135]
	s_branch .Lp0n_wd_l4

; DI u32x4 pk8(f32x4 a, f32x4 b) { u32x4 w; w.x = pk2(a[0], a[1]); w.y = pk2(a[2], a[3]); w.z = pk2(b[0], b[1]); w.w = pk2(b[2], b[3]); return w; }
; DI float wave_sum(float v) { for (int o = 32; o >= 1; o >>= 1) v += __shfl_xor(v, o); return v; }
; DI void rownorm_store(const f32x4 (&v)[4], const float* w, bf16_t* o, int lane) {
;   float ss = 0.f;
; #pragma unroll
;   for (int e = 0; e < 4; ++e) ss += v[e][0] * v[e][0] + v[e][1] * v[e][1] + v[e][2] * v[e][2] + v[e][3] * v[e][3];
;   ss = wave_sum(ss); const float rstd = rsqrtf(ss * (1.f / 1024.f) + EPS);
; #pragma unroll
;   for (int i = 0; i < 2; ++i) { const f32x4 w0 = *(const f32x4*)(w + RCOL(2 * i)), w1 = *(const f32x4*)(w + RCOL(2 * i + 1));
;     *(u32x4*)(o + i * 512 + lane * 8) = pk8(v[2 * i] * rstd * w0, v[2 * i + 1] * rstd * w1); }
; }
; DI void phase_prep(const Params& p, ldsp lds, int tid_) {
;     ...
;     for (int r = wv; r < NR; r += nwv) {
;       const int rn = r + 2 * nwv; f32x4 v2[4];
;       const int rc = rn < NR ? rn : r;
; #pragma unroll
;       for (int i = 0; i < 4; ++i) v2[i] = *(const f32x4*)(prep_row_src(p, rc) + RCOL(i));
;       if (r < T) rownorm_store(v0, p.in[8], (bf16_t*)(ws + B_XA) + (size_t)r * D, lane);
;       else rownorm_store(v0, p.in[23], (bf16_t*)(ws + B_MN) + (size_t)(r - T) * D, lane);
; #pragma unroll
;       for (int i = 0; i < 4; ++i) { v0[i] = v1[i]; v1[i] = v2[i]; }
.Lp0n_wd_l4:
	v_cvt_pk_bf16_f32 v200, v120, v121
	v_cvt_pk_bf16_f32 v201, v122, v123
	v_cvt_pk_bf16_f32 v202, v124, v125
	v_cvt_pk_bf16_f32 v203, v126, v127
	v_cvt_pk_bf16_f32 v204, v128, v129
	v_cvt_pk_bf16_f32 v205, v130, v131
	v_cvt_pk_bf16_f32 v206, v132, v133
	v_cvt_pk_bf16_f32 v207, v134, v135
	global_store_dwordx2 v85, v[200:201], s[90:91]
	global_store_dwordx2 v85, v[202:203], s[90:91] offset:512
	global_store_dwordx2 v85, v[204:205], s[90:91] offset:1024
	global_store_dwordx2 v85, v[206:207], s[90:91] offset:1536
	s_add_u32 s74, s74, s58
	s_cmp_lt_u32 s74, 0x4a00
	s_cbranch_scc0 .Lp0n_done
	s_cmp_lt_u32 s75, 0x4000
	s_cselect_b32 s88, s76, s78
	s_cselect_b32 s89, s77, s79
	s_cselect_b32 s92, 0, 0x4000
	s_cmp_lt_u32 s75, 0x4200
	s_cselect_b32 s88, s88, s80
	s_cselect_b32 s89, s89, s81
	s_cselect_b32 s92, s92, 0x4200
	s_sub_u32 s92, s75, s92
	s_cmp_lt_u32 s75, 0x4a00
	s_cselect_b32 s92, s92, 0
	s_lshl_b32 s93, s92, 12
	s_add_u32 s88, s88, s93
	s_addc_u32 s89, s89, 0
	s_add_u32 s75, s75, s58
	global_load_dwordx4 v[120:123], v84, s[88:89] nt
	global_load_dwordx4 v[124:127], v84, s[88:89] offset:1024 nt
	global_load_dwordx4 v[128:131], v84, s[88:89] offset:2048 nt
	global_load_dwordx4 v[132:135], v84, s[88:89] offset:3072 nt
	s_waitcnt vmcnt(24)
	v_pk_mul_f32 v[192:193], v[136:137], v[136:137]
	v_pk_fma_f32 v[192:193], v[138:139], v[138:139], v[192:193]
	v_pk_fma_f32 v[192:193], v[140:141], v[140:141], v[192:193]
	v_pk_fma_f32 v[192:193], v[142:143], v[142:143], v[192:193]
	v_pk_fma_f32 v[192:193], v[144:145], v[144:145], v[192:193]
	v_pk_fma_f32 v[192:193], v[146:147], v[146:147], v[192:193]
	v_pk_fma_f32 v[192:193], v[148:149], v[148:149], v[192:193]
	v_pk_fma_f32 v[192:193], v[150:151], v[150:151], v[192:193]
	s_cmp_lt_u32 s74, 0x4200
	s_cselect_b32 s90, s66, s68
	s_cselect_b32 s91, s67, s69
	s_cselect_b32 s92, 0, 0x4200
	s_sub_u32 s92, s74, s92
	s_lshl_b32 s92, s92, 11
	s_add_u32 s90, s90, s92
	s_addc_u32 s91, s91, 0
	v_add_f32_e32 v194, v192, v193
	ds_bpermute_b32 v195, v184, v194
	s_waitcnt lgkmcnt(0)
	v_add_f32_e32 v194, v194, v195
	ds_bpermute_b32 v195, v185, v194
	s_waitcnt lgkmcnt(0)
	v_add_f32_e32 v194, v194, v195
	ds_bpermute_b32 v195, v186, v194
	s_waitcnt lgkmcnt(0)
	v_add_f32_e32 v194, v194, v195
	ds_bpermute_b32 v195, v187, v194
	s_waitcnt lgkmcnt(0)
	v_add_f32_e32 v194, v194, v195
	ds_bpermute_b32 v195, v188, v194
	s_waitcnt lgkmcnt(0)
	v_add_f32_e32 v194, v194, v195
	ds_bpermute_b32 v195, v189, v194
	s_waitcnt lgkmcnt(0)
	v_add_f32_e32 v194, v194, v195
	v_fmamk_f32 v196, v194, 0x3a800000, v190
	v_mul_f32_e32 v197, 0x4b800000, v196
	v_cmp_gt_f32_e32 vcc, s12, v196
	s_nop 1
	v_cndmask_b32_e32 v196, v196, v197, vcc
	v_rsq_f32_e32 v197, v196
	s_nop 0
	v_mul_f32_e32 v196, 0x45800000, v197
	v_cndmask_b32_e32 v198, v197, v196, vcc
	v_pk_mul_f32 v[136:137], v[136:137], v[198:199] op_sel_hi:[1,0]
	v_pk_mul_f32 v[138:139], v[138:139], v[198:199] op_sel_hi:[1,0]
	v_pk_mul_f32 v[140:141], v[140:141], v[198:199] op_sel_hi:[1,0]
	v_pk_mul_f32 v[142:143], v[142:143], v[198:199] op_sel_hi:[1,0]
	v_pk_mul_f32 v[144:145], v[144:145], v[198:199] op_sel_hi:[1,0]
	v_pk_mul_f32 v[146:147], v[146:147], v[198:199] op_sel_hi:[1,0]
	v_pk_mul_f32 v[148:149], v[148:149], v[198:199] op_sel_hi:[1,0]
	v_pk_mul_f32 v[150:151], v[150:151], v[198:199] op_sel_hi:[1,0]
	s_cmp_lt_u32 s74, 0x4200
	s_cbranch_scc0 .Lp0n_wb_l5
	v_pk_mul_f32 v[136:137], v[88:89], v[136:137]
	v_pk_mul_f32 v[138:139], v[90:91], v[138:139]
	v_pk_mul_f32 v[140:141], v[92:93], v[140:141]
	v_pk_mul_f32 v[142:143], v[94:95], v[142:143]
	v_pk_mul_f32 v[144:145], v[96:97], v[144:145]
	v_pk_mul_f32 v[146:147], v[98:99], v[146:147]
	v_pk_mul_f32 v[148:149], v[100:101], v[148:149]
	v_pk_mul_f32 v[150:151], v[102:103], v[150:151]
	s_branch .Lp0n_wd_l5

; DI u32x4 pk8(f32x4 a, f32x4 b) { u32x4 w; w.x = pk2(a[0], a[1]); w.y = pk2(a[2], a[3]); w.z = pk2(b[0], b[1]); w.w = pk2(b[2], b[3]); return w; }
; DI float wave_sum(float v) { for (int o = 32; o >= 1; o >>= 1) v += __shfl_xor(v, o); return v; }
; DI void rownorm_store(const f32x4 (&v)[4], const float* w, bf16_t* o, int lane) {
;   float ss = 0.f;
; #pragma unroll
;   for (int e = 0; e < 4; ++e) ss += v[e][0] * v[e][0] + v[e][1] * v[e][1] + v[e][2] * v[e][2] + v[e][3] * v[e][3];
;   ss = wave_sum(ss); const float rstd = rsqrtf(ss * (1.f / 1024.f) + EPS);
; #pragma unroll
;   for (int i = 0; i < 2; ++i) { const f32x4 w0 = *(const f32x4*)(w + RCOL(2 * i)), w1 = *(const f32x4*)(w + RCOL(2 * i + 1));
;     *(u32x4*)(o + i * 512 + lane * 8) = pk8(v[2 * i] * rstd * w0, v[2 * i + 1] * rstd * w1); }
; }
; DI void phase_prep(const Params& p, ldsp lds, int tid_) {
;     ...
;     for (int r = wv; r < NR; r += nwv) {
;       const int rn = r + 2 * nwv; f32x4 v2[4];
;       const int rc = rn < NR ? rn : r;
; #pragma unroll
;       for (int i = 0; i < 4; ++i) v2[i] = *(const f32x4*)(prep_row_src(p, rc) + RCOL(i));
;       if (r < T) rownorm_store(v0, p.in[8], (bf16_t*)(ws + B_XA) + (size_t)r * D, lane);
;       else rownorm_store(v0, p.in[23], (bf16_t*)(ws + B_MN) + (size_t)(r - T) * D, lane);
; #pragma unroll
;       for (int i = 0; i < 4; ++i) { v0[i] = v1[i]; v1[i] = v2[i]; }
.Lp0n_wd_l5:
	v_cvt_pk_bf16_f32 v200, v136, v137
	v_cvt_pk_bf16_f32 v201, v138, v139
	v_cvt_pk_bf16_f32 v202, v140, v141
	v_cvt_pk_bf16_f32 v203, v142, v143
	v_cvt_pk_bf16_f32 v204, v144, v145
	v_cvt_pk_bf16_f32 v205, v146, v147
	v_cvt_pk_bf16_f32 v206, v148, v149
	v_cvt_pk_bf16_f32 v207, v150, v151
	global_store_dwordx2 v85, v[200:201], s[90:91]
	global_store_dwordx2 v85, v[202:203], s[90:91] offset:512
	global_store_dwordx2 v85, v[204:205], s[90:91] offset:1024
	global_store_dwordx2 v85, v[206:207], s[90:91] offset:1536
	s_add_u32 s74, s74, s58
	s_cmp_lt_u32 s74, 0x4a00
	s_cbranch_scc0 .Lp0n_done
	s_cmp_lt_u32 s75, 0x4000
	s_cselect_b32 s88, s76, s78
	s_cselect_b32 s89, s77, s79
	s_cselect_b32 s92, 0, 0x4000
	s_cmp_lt_u32 s75, 0x4200
	s_cselect_b32 s88, s88, s80
	s_cselect_b32 s89, s89, s81
	s_cselect_b32 s92, s92, 0x4200
	s_sub_u32 s92, s75, s92
	s_cmp_lt_u32 s75, 0x4a00
	s_cselect_b32 s92, s92, 0
	s_lshl_b32 s93, s92, 12
	s_add_u32 s88, s88, s93
	s_addc_u32 s89, s89, 0
	s_add_u32 s75, s75, s58
	global_load_dwordx4 v[136:139], v84, s[88:89] nt
	global_load_dwordx4 v[140:143], v84, s[88:89] offset:1024 nt
	global_load_dwordx4 v[144:147], v84, s[88:89] offset:2048 nt
	global_load_dwordx4 v[148:151], v84, s[88:89] offset:3072 nt
	s_waitcnt vmcnt(24)
	v_pk_mul_f32 v[192:193], v[152:153], v[152:153]
	v_pk_fma_f32 v[192:193], v[154:155], v[154:155], v[192:193]
	v_pk_fma_f32 v[192:193], v[156:157], v[156:157], v[192:193]
	v_pk_fma_f32 v[192:193], v[158:159], v[158:159], v[192:193]
	v_pk_fma_f32 v[192:193], v[160:161], v[160:161], v[192:193]
	v_pk_fma_f32 v[192:193], v[162:163], v[162:163], v[192:193]
	v_pk_fma_f32 v[192:193], v[164:165], v[164:165], v[192:193]
	v_pk_fma_f32 v[192:193], v[166:167], v[166:167], v[192:193]
	s_cmp_lt_u32 s74, 0x4200
	s_cselect_b32 s90, s66, s68
	s_cselect_b32 s91, s67, s69
	s_cselect_b32 s92, 0, 0x4200
	s_sub_u32 s92, s74, s92
	s_lshl_b32 s92, s92, 11
	s_add_u32 s90, s90, s92
	s_addc_u32 s91, s91, 0
	v_add_f32_e32 v194, v192, v193
	ds_bpermute_b32 v195, v184, v194
	s_waitcnt lgkmcnt(0)
	v_add_f32_e32 v194, v194, v195
	ds_bpermute_b32 v195, v185, v194
	s_waitcnt lgkmcnt(0)
	v_add_f32_e32 v194, v194, v195
	ds_bpermute_b32 v195, v186, v194
	s_waitcnt lgkmcnt(0)
	v_add_f32_e32 v194, v194, v195
	ds_bpermute_b32 v195, v187, v194
	s_waitcnt lgkmcnt(0)
	v_add_f32_e32 v194, v194, v195
	ds_bpermute_b32 v195, v188, v194
	s_waitcnt lgkmcnt(0)
	v_add_f32_e32 v194, v194, v195
	ds_bpermute_b32 v195, v189, v194
	s_waitcnt lgkmcnt(0)
	v_add_f32_e32 v194, v194, v195
	v_fmamk_f32 v196, v194, 0x3a800000, v190
	v_mul_f32_e32 v197, 0x4b800000, v196
	v_cmp_gt_f32_e32 vcc, s12, v196
	s_nop 1
	v_cndmask_b32_e32 v196, v196, v197, vcc
	v_rsq_f32_e32 v197, v196
	s_nop 0
	v_mul_f32_e32 v196, 0x45800000, v197
	v_cndmask_b32_e32 v198, v197, v196, vcc
	v_pk_mul_f32 v[152:153], v[152:153], v[198:199] op_sel_hi:[1,0]
	v_pk_mul_f32 v[154:155], v[154:155], v[198:199] op_sel_hi:[1,0]
	v_pk_mul_f32 v[156:157], v[156:157], v[198:199] op_sel_hi:[1,0]
	v_pk_mul_f32 v[158:159], v[158:159], v[198:199] op_sel_hi:[1,0]
	v_pk_mul_f32 v[160:161], v[160:161], v[198:199] op_sel_hi:[1,0]
	v_pk_mul_f32 v[162:163], v[162:163], v[198:199] op_sel_hi:[1,0]
	v_pk_mul_f32 v[164:165], v[164:165], v[198:199] op_sel_hi:[1,0]
	v_pk_mul_f32 v[166:167], v[166:167], v[198:199] op_sel_hi:[1,0]
	s_cmp_lt_u32 s74, 0x4200
	s_cbranch_scc0 .Lp0n_wb_l6
	v_pk_mul_f32 v[152:153], v[88:89], v[152:153]
	v_pk_mul_f32 v[154:155], v[90:91], v[154:155]
	v_pk_mul_f32 v[156:157], v[92:93], v[156:157]
	v_pk_mul_f32 v[158:159], v[94:95], v[158:159]
	v_pk_mul_f32 v[160:161], v[96:97], v[160:161]
	v_pk_mul_f32 v[162:163], v[98:99], v[162:163]
	v_pk_mul_f32 v[164:165], v[100:101], v[164:165]
	v_pk_mul_f32 v[166:167], v[102:103], v[166:167]
	s_branch .Lp0n_wd_l6

; DI void phase_prep(const Params& p, ldsp lds, int tid_) {
;     ...
;     for (int r = wv; r < NR; r += nwv) {
;       const int rn = r + 2 * nwv; f32x4 v2[4];
;       const int rc = rn < NR ? rn : r;
; #pragma unroll
;       for (int i = 0; i < 4; ++i) v2[i] = *(const f32x4*)(prep_row_src(p, rc) + RCOL(i));
;       if (r < T) rownorm_store(v0, p.in[8], (bf16_t*)(ws + B_XA) + (size_t)r * D, lane);
;       else rownorm_store(v0, p.in[23], (bf16_t*)(ws + B_MN) + (size_t)(r - T) * D, lane);
; #pragma unroll
;       for (int i = 0; i < 4; ++i) { v0[i] = v1[i]; v1[i] = v2[i]; }
;     }
; DI void xcd_barrier(const XcdBarrier& b) {
;   asm volatile("s_waitcnt vmcnt(0)" ::: "memory");
;   __syncthreads();
;   if (threadIdx.x == 0) {
;     unsigned* bar = b.bar;
;     __builtin_amdgcn_s_waitcnt(0);
;     unsigned nloc = b.st[0], nx = b.st[1];
;     if (nloc == 0u) { xcd_barrier_complete(bar, b.x, nloc, nx); b.st[0] = nloc; b.st[1] = nx; }
.Lp0n_wd_l6:
	v_cvt_pk_bf16_f32 v200, v152, v153
	v_cvt_pk_bf16_f32 v201, v154, v155
	v_cvt_pk_bf16_f32 v202, v156, v157
	v_cvt_pk_bf16_f32 v203, v158, v159
	v_cvt_pk_bf16_f32 v204, v160, v161
	v_cvt_pk_bf16_f32 v205, v162, v163
	v_cvt_pk_bf16_f32 v206, v164, v165
	v_cvt_pk_bf16_f32 v207, v166, v167
	global_store_dwordx2 v85, v[200:201], s[90:91]
	global_store_dwordx2 v85, v[202:203], s[90:91] offset:512
	global_store_dwordx2 v85, v[204:205], s[90:91] offset:1024
	global_store_dwordx2 v85, v[206:207], s[90:91] offset:1536
	s_add_u32 s74, s74, s58
	s_branch .Lp0n_loop
.Lp0n_done:
	s_mov_b64 s[4:5], exec
.LBB0_139:
	s_or_b64 exec, exec, s[4:5]
	s_waitcnt vmcnt(0)
	s_waitcnt lgkmcnt(0)
	s_barrier
	s_and_saveexec_b64 s[0:1], s[64:65]
	s_xor_b64 s[4:5], exec, s[0:1]
	s_cbranch_execz .LBB0_222
	s_waitcnt vmcnt(0)
	v_mov_b32_e32 v0, 0
	s_waitcnt vmcnt(0) expcnt(0) lgkmcnt(0)
	ds_read_b32 v2, v0
	ds_read_b32 v1, v0 offset:4
	s_waitcnt lgkmcnt(1)
	v_cmp_ne_u32_e32 vcc, 0, v2
	s_cbranch_vccnz .LBB0_155
	s_add_u32 s6, s42, 0x18e68200
	s_addc_u32 s7, s43, 0
	s_add_u32 s8, s42, 0x18e68400
	s_addc_u32 s9, s43, 0
	s_add_u32 s10, s42, 0x18e68500
	s_addc_u32 s11, s43, 0
	s_add_u32 s12, s42, 0x18e68600
	s_addc_u32 s13, s43, 0
	s_add_u32 s14, s42, 0x18e68700
	s_addc_u32 s15, s43, 0
	s_add_u32 s16, s42, 0x18e68800
	s_addc_u32 s17, s43, 0
	s_add_u32 s18, s42, 0x18e68900
	s_addc_u32 s19, s43, 0
	s_add_u32 s20, s42, 0x18e68a00
	s_addc_u32 s21, s43, 0
	s_add_u32 s22, s42, 0x18e68b00
	s_addc_u32 s23, s43, 0
	s_add_u32 s24, s42, 0x18e68c00
	s_addc_u32 s25, s43, 0
	s_add_u32 s26, s42, 0x18e68d00
	s_addc_u32 s27, s43, 0
	s_add_u32 s28, s42, 0x18e68e00
	s_addc_u32 s29, s43, 0
	s_add_u32 s30, s42, 0x18e68f00
	s_addc_u32 s31, s43, 0
	s_add_u32 s34, s42, 0x18e69000
	s_addc_u32 s35, s43, 0
	s_add_u32 s36, s42, 0x18e69100
	s_addc_u32 s37, s43, 0
	s_add_u32 s38, s42, 0x18e69200
	s_addc_u32 s39, s43, 0
	s_add_u32 s44, s42, 0x18e69300
	s_addc_u32 s45, s43, 0
	s_mov_b32 s0, 1
	s_branch .LBB0_143

; #define LAS __attribute__((address_space(3)))
; DI unsigned pk2(float lo, float hi) { f32x2 v = {lo, hi}; return __builtin_bit_cast(unsigned, __builtin_convertvector(v, bf16x2v)); }
; DI void ssd_chain(const Params& p, int b, int h, bool sample, ldsp lds, int tid_) {
;     ...
;   const int nchunks = sample ? 1 : 32, ntok = sample ? 4 : 64, rowbase = sample ? TP + b * 4 : b * 2048, g = h >> 2;
;   ldsp MM = lds, XW = lds + 9216, SB = lds + 18432;
;   const float Dh = p.in[18][h];
;   f32x4 Sacc[4];
;   float* sout = p.out + (sample ? O_SSMS : O_SSMP) + (size_t)(b * 8 + h) * 8192;
; #pragma unroll
;   for (int pt = 0; pt < 4; ++pt) {
;     if (sample) Sacc[pt] = *(const f32x4*)(p.in[4] + (size_t)(b * 8 + h) * 8192 + (pt * 16 + fr) * 128 + wid * 16 + 4 * fq);
;     else Sacc[pt] = (f32x4){0.f, 0.f, 0.f, 0.f};
;     u32x2 w; w.x = pk2(Sacc[pt][0], Sacc[pt][1]); w.y = pk2(Sacc[pt][2], Sacc[pt][3]);
;     *(LAS u32x2*)(SB + (pt * 16 + fr) * 272 + (wid * 16 + 4 * fq) * 2) = w;
;   }
.LBB0_830:
	s_cmpk_gt_i32 s41, 0x1ff
	s_mov_b64 s[4:5], -1
	s_cbranch_scc0 .LBB0_868
	s_add_i32 s4, s41, 0xfffffe00
	v_mov_b32_e32 v51, v212
	s_lshr_b32 s4, s4, 3
	s_and_b32 s46, s41, 7
	s_lshl_b32 s47, s4, 2
	v_readfirstlane_b32 s49, v51
	s_ashr_i32 s48, s49, 6
	s_lshl_b32 s4, s4, 16
	s_lshl_b32 s5, s46, 13
	s_or_b32 s12, s4, s5
	s_lshl_b32 s45, s48, 5
	s_lshl_b32 s24, s48, 4
	s_addk_i32 s47, 0x4000
	s_lshl_b32 s14, s46, 2
	s_add_i32 s44, s45, 16
	s_ashr_i32 s25, s24, 31
	s_lshl_b64 s[26:27], s[12:13], 2
	v_and_b32_e32 v52, 15, v51
	s_waitcnt lgkmcnt(0)
	s_add_u32 s4, s10, s26
	s_addc_u32 s5, s11, s27
	v_lshlrev_b32_e32 v0, 9, v52
	v_lshl_add_u64 v[2:3], s[4:5], 0, v[0:1]
	v_lshl_add_u64 v[4:5], s[24:25], 2, v[2:3]
	v_and_b32_e32 v2, 48, v51
	v_mov_b32_e32 v3, v1
	v_lshl_add_u64 v[4:5], v[4:5], 0, v[2:3]
	v_add_co_u32_e32 v6, vcc, s34, v4
	v_readlane_b32 s4, v248, 20
	s_nop 0
	v_addc_co_u32_e32 v7, vcc, 0, v5, vcc
	global_load_dwordx4 v[16:19], v[4:5], off nt
	global_load_dwordx4 v[12:15], v[6:7], off nt
	v_add_co_u32_e32 v6, vcc, s7, v4
	v_mov_b32_e32 v0, s14
	s_nop 0
	v_addc_co_u32_e32 v7, vcc, 0, v5, vcc
	v_add_co_u32_e32 v4, vcc, s35, v4
	global_load_dwordx4 v[8:11], v[6:7], off nt
	s_nop 0
	v_addc_co_u32_e32 v5, vcc, 0, v5, vcc
	global_load_dwordx4 v[4:7], v[4:5], off nt
	v_readlane_b32 s5, v248, 21
	s_waitcnt vmcnt(4)
	v_bfe_u32 v54, v51, 4, 2
	v_lshlrev_b32_e32 v49, 3, v54
	v_mul_u32_u24_e32 v48, 0x110, v52
	v_add3_u32 v21, s44, v49, v48
	v_ashrrev_i32_e32 v3, 3, v51
	global_load_dword v44, v0, s[4:5]
	v_and_b32_e32 v53, 7, v51
	v_mov_b32_e32 v20, 0
	v_mov_b32_e32 v24, 0
	v_mov_b32_e32 v25, 0
	v_mov_b32_e32 v26, 0
	v_cmp_gt_i32_e32 vcc, 4, v3
	v_add_u32_e32 v28, s47, v3
	v_lshlrev_b32_e32 v0, 4, v53
	v_mov_b32_e32 v27, 0
	s_waitcnt vmcnt(4)
	v_cvt_pk_bf16_f32 v22, v16, v17
	v_cvt_pk_bf16_f32 v23, v18, v19
	ds_write_b64 v21, v[22:23] offset:18432
	s_waitcnt vmcnt(3)
	v_cvt_pk_bf16_f32 v22, v12, v13
	v_cvt_pk_bf16_f32 v23, v14, v15
	s_waitcnt vmcnt(2)
	v_cvt_pk_bf16_f32 v30, v8, v9
	v_cvt_pk_bf16_f32 v31, v10, v11
	ds_write_b64 v21, v[22:23] offset:22784
	ds_write_b64 v21, v[30:31] offset:27136
	s_waitcnt vmcnt(1)
	v_cvt_pk_bf16_f32 v22, v4, v5
	v_cvt_pk_bf16_f32 v23, v6, v7
	ds_write_b64 v21, v[22:23] offset:31488
	s_and_saveexec_b64 s[4:5], vcc
	s_cbranch_execz .LBB0_833
	v_ashrrev_i32_e32 v29, 31, v28
	v_lshlrev_b64 v[22:23], 11, v[28:29]
	v_lshl_add_u64 v[22:23], s[62:63], 0, v[22:23]
	s_lshl_b32 s12, s46, 7
	v_lshl_add_u64 v[22:23], v[22:23], 0, s[12:13]
	v_lshl_add_u64 v[22:23], v[22:23], 0, v[0:1]
	global_load_dwordx4 v[24:27], v[22:23], off

; #define LAS __attribute__((address_space(3)))
; DI unsigned pk2(float lo, float hi) { f32x2 v = {lo, hi}; return __builtin_bit_cast(unsigned, __builtin_convertvector(v, bf16x2v)); }
; DI void gla_chain(const Params& p, int b, int h, bool sample, ldsp lds, int tid_) {
;     ...
;   const int nchunks = sample ? 1 : 32, ntok = sample ? 4 : 64, rowbase = sample ? TP + b * 4 : b * 2048, item0 = sample ? 256 + b : b * 32;
;   ldsp VV = lds, QT = lds + 17408, KT = lds + 26624, KD = lds + 35840, ATT = lds + 45056, SB = lds + 54272, EB = lds + 71680;
;   f32x4 Sacc[4];
;   float* sout = p.out + (sample ? O_GLAS : O_GLAP) + (size_t)(b * 4 + h) * 8192;
; #pragma unroll
;   for (int kt = 0; kt < 4; ++kt) {
;     if (sample) Sacc[kt] = *(const f32x4*)(p.in[3] + (size_t)(b * 4 + h) * 8192 + (kt * 16 + fr) * 128 + wid * 16 + 4 * fq);
;     else Sacc[kt] = (f32x4){0.f, 0.f, 0.f, 0.f};
;     u32x2 w; w.x = pk2(Sacc[kt][0], Sacc[kt][1]); w.y = pk2(Sacc[kt][2], Sacc[kt][3]);
;     *(LAS u32x2*)(SB + (kt * 16 + fr) * 272 + (wid * 16 + 4 * fq) * 2) = w;
;   }
.LBB0_868:
	s_and_b64 vcc, exec, s[4:5]
	s_cbranch_vccz .LBB0_829
	v_mov_b32_e32 v36, v212
	s_and_b32 s26, s41, 3
	v_readfirstlane_b32 s30, v36
	s_ashr_i32 s29, s30, 6
	s_lshl_b32 s27, s29, 5
	s_lshl_b32 s14, s29, 4
	v_and_b32_e32 v39, 15, v36
	s_and_b32 s28, s41, -4
	s_add_i32 s12, s27, 16
	s_ashr_i32 s15, s14, 31
	v_and_b32_e32 v41, 48, v36
	v_lshl_or_b32 v0, v39, 9, v41
	s_waitcnt lgkmcnt(0)
	s_add_u32 s4, s8, s18
	v_lshl_add_u64 v[34:35], s[14:15], 2, v[0:1]
	s_addc_u32 s5, s9, s19
	v_lshl_add_u64 v[2:3], s[4:5], 0, v[34:35]
	v_add_co_u32_e32 v4, vcc, s34, v2
	v_bfe_u32 v43, v36, 4, 2
	s_nop 0
	v_addc_co_u32_e32 v5, vcc, 0, v3, vcc
	global_load_dwordx4 v[14:17], v[2:3], off nt
	global_load_dwordx4 v[10:13], v[4:5], off nt
	v_add_co_u32_e32 v4, vcc, s7, v2
	v_ashrrev_i32_e32 v44, 3, v36
	s_nop 0
	v_addc_co_u32_e32 v5, vcc, 0, v3, vcc
	v_add_co_u32_e32 v2, vcc, s35, v2
	global_load_dwordx4 v[6:9], v[4:5], off nt
	s_nop 0
	v_addc_co_u32_e32 v3, vcc, 0, v3, vcc
	global_load_dwordx4 v[2:5], v[2:3], off nt
	s_addk_i32 s28, 0x4000
	v_lshlrev_b32_e32 v42, 3, v43
	v_add_u32_e32 v20, s28, v44
	v_and_b32_e32 v46, 7, v36
	v_add_u32_e32 v40, s12, v42
	v_ashrrev_i32_e32 v21, 31, v20
	v_mad_u32_u24 v0, v39, s17, v45
	v_lshlrev_b32_e32 v19, 3, v46
	v_mad_u32_u24 v25, v39, s17, v40
	s_lshl_b32 s31, s26, 6
	v_lshlrev_b64 v[26:27], 8, v[20:21]
	v_mov_b32_e32 v18, 0
	v_mov_b32_e32 v22, 0
	v_mov_b32_e32 v23, 0
	v_mov_b32_e32 v24, 0
	v_cmp_gt_i32_e32 vcc, 4, v44
	v_add_u32_e32 v38, v40, v0
	v_or3_b32 v26, v26, v19, s31
	s_waitcnt vmcnt(3)
	v_cvt_pk_bf16_f32 v20, v14, v15
	v_cvt_pk_bf16_f32 v21, v16, v17
	ds_write_b64 v25, v[20:21] offset:54272
	s_waitcnt vmcnt(2)
	v_cvt_pk_bf16_f32 v20, v10, v11
	v_cvt_pk_bf16_f32 v21, v12, v13
	v_mov_b32_e32 v25, 0
	s_waitcnt vmcnt(1)
	v_cvt_pk_bf16_f32 v28, v6, v7
	v_cvt_pk_bf16_f32 v29, v8, v9
	s_waitcnt vmcnt(0)
	v_cvt_pk_bf16_f32 v30, v2, v3
	v_cvt_pk_bf16_f32 v31, v4, v5
	ds_write_b64 v38, v[20:21] offset:54272
	ds_write_b64 v38, v[28:29] offset:58624
	ds_write_b64 v38, v[30:31] offset:62976
	s_and_saveexec_b64 s[4:5], vcc
	s_cbranch_execz .LBB0_871
	v_lshl_add_u64 v[20:21], v[26:27], 1, s[70:71]
	global_load_dwordx4 v[22:25], v[20:21], off

; #define LAS __attribute__((address_space(3)))
; DI void tr_weight(const float* W, bf16_t* Wt, const int K, const int N, const int ntn, const int drow_off, const int gu, const int rot, ldsp lds, int tid, const int G, const int lb) {
;   LAS float* tile = (LAS float*)lds;
;   const int nn = tid & 63, kb = tid >> 6, n2 = tid >> 3, kq = tid & 7;
;   const int ktiles = K / 64, ntiles = ntn * ktiles;
;   int task = (lb + G - (rot % G)) % G;
;   float pre[8];
;   if (task < ntiles) { const int n = (task / ktiles) * 64 + nn, k0 = (task % ktiles) * 64;
; #pragma unroll
;     for (int i = 0; i < 8; ++i) pre[i] = (n < N) ? W[(size_t)(k0 + kb + 8 * i) * N + n] : 0.f; }
.LBB0_887:
	s_abs_i32 s0, s6
	v_cvt_f32_u32_e32 v0, s0
	v_lshlrev_b32_e32 v1, 3, v212
	v_and_b32_e32 v19, 56, v1
	s_sub_i32 s3, 0, s0
	v_rcp_iflag_f32_e32 v1, v0
	s_add_i32 s1, s16, s6
	s_abs_i32 s5, s1
	s_ashr_i32 s4, s1, 31
	v_mul_f32_e32 v1, 0x4f7ffffe, v1
	v_cvt_u32_f32_e32 v1, v1
	v_and_b32_e32 v14, 63, v212
	v_lshrrev_b32_e32 v18, 6, v212
	v_lshrrev_b32_e32 v15, 3, v212
	v_readfirstlane_b32 s7, v1
	s_mul_i32 s3, s3, s7
	s_mul_hi_u32 s3, s7, s3
	s_add_i32 s3, s7, s3
	s_mul_hi_u32 s7, s5, s3
	s_mul_i32 s7, s7, s0
	s_sub_i32 s5, s5, s7
	s_sub_i32 s7, s5, s0
	s_cmp_ge_u32 s5, s0
	s_cselect_b32 s5, s7, s5
	s_sub_i32 s7, s5, s0
	s_cmp_ge_u32 s5, s0
	s_cselect_b32 s5, s7, s5
	s_xor_b32 s5, s5, s4
	s_sub_i32 s7, s5, s4
	v_readlane_b32 s24, v248, 10
	v_lshl_add_u32 v20, v14, 2, 16
	v_lshl_add_u32 v16, v15, 2, 16
	v_mov_b32_e32 v0, 0
	v_mul_u32_u24_e32 v21, 0x104, v18
	s_cmpk_lt_i32 s7, 0x100
	v_mul_u32_u24_e32 v17, 0x104, v19
	v_readlane_b32 s25, v248, 11
	v_readlane_b32 s26, v248, 12
	v_readlane_b32 s27, v248, 13
	v_readlane_b32 s28, v248, 14
	v_readlane_b32 s29, v248, 15
	v_readlane_b32 s30, v248, 16
	v_readlane_b32 s31, v248, 17
	s_cbranch_scc0 .LBB0_924
	s_ashr_i32 s4, s7, 31
	s_lshr_b32 s4, s4, 28
	s_load_dwordx2 s[8:9], s[72:73], 0xa0
	s_add_i32 s4, s7, s4
	s_lshl_b32 s5, s4, 2
	s_andn2_b32 s5, s5, 63
	s_and_b32 s4, s4, 0x3fffff0
	v_or_b32_e32 v2, s5, v14
	s_sub_i32 s10, s7, s4
	s_movk_i32 s4, 0x400
	v_lshl_or_b32 v10, s10, 6, v18
	v_ashrrev_i32_e32 v3, 31, v2
	v_cmp_gt_i32_e64 s[4:5], s4, v2
	s_waitcnt lgkmcnt(0)
	v_lshl_add_u64 v[12:13], v[2:3], 2, s[8:9]
	v_ashrrev_i32_e32 v11, 31, v10
	s_and_saveexec_b64 s[10:11], s[4:5]
	s_cbranch_execz .LBB0_890
	v_lshlrev_b64 v[0:1], 12, v[10:11]
	v_lshl_add_u64 v[0:1], v[12:13], 0, v[0:1]
	global_load_dword v0, v[0:1], off nt
.LBB0_890:
	s_or_b64 exec, exec, s[10:11]
	v_mov_b32_e32 v2, 0
	v_mov_b32_e32 v1, 0
	s_and_saveexec_b64 s[10:11], s[4:5]
	s_cbranch_execz .LBB0_892
	v_lshlrev_b64 v[4:5], 12, v[10:11]
	v_lshl_add_u64 v[4:5], v[12:13], 0, v[4:5]
	v_add_co_u32_e32 v4, vcc, 0x8000, v4
	s_nop 1
	v_addc_co_u32_e32 v5, vcc, 0, v5, vcc
	global_load_dword v1, v[4:5], off nt
.LBB0_892:
	s_or_b64 exec, exec, s[10:11]
	s_and_saveexec_b64 s[10:11], s[4:5]
	s_cbranch_execz .LBB0_894
	v_or_b32_e32 v2, 16, v10
	v_ashrrev_i32_e32 v3, 31, v2
	v_lshlrev_b64 v[2:3], 12, v[2:3]
	v_lshl_add_u64 v[2:3], v[12:13], 0, v[2:3]
	global_load_dword v2, v[2:3], off nt
.LBB0_894:
	s_or_b64 exec, exec, s[10:11]
	v_mov_b32_e32 v4, 0
	v_mov_b32_e32 v3, 0
	s_and_saveexec_b64 s[10:11], s[4:5]
	s_cbranch_execz .LBB0_896
	v_lshlrev_b64 v[6:7], 12, v[10:11]
	v_lshl_add_u64 v[6:7], v[12:13], 0, v[6:7]
	v_add_co_u32_e32 v6, vcc, 0x18000, v6
	s_nop 1
	v_addc_co_u32_e32 v7, vcc, 0, v7, vcc
	global_load_dword v3, v[6:7], off nt
.LBB0_896:
	s_or_b64 exec, exec, s[10:11]
	s_and_saveexec_b64 s[10:11], s[4:5]
	s_cbranch_execz .LBB0_898
	v_or_b32_e32 v4, 32, v10
	v_ashrrev_i32_e32 v5, 31, v4
	v_lshlrev_b64 v[4:5], 12, v[4:5]
	v_lshl_add_u64 v[4:5], v[12:13], 0, v[4:5]
	global_load_dword v4, v[4:5], off nt
.LBB0_898:
	s_or_b64 exec, exec, s[10:11]
	v_mov_b32_e32 v6, 0
	v_mov_b32_e32 v5, 0
	s_and_saveexec_b64 s[10:11], s[4:5]
	s_cbranch_execz .LBB0_900
	v_lshlrev_b64 v[8:9], 12, v[10:11]
	v_lshl_add_u64 v[8:9], v[12:13], 0, v[8:9]
	v_add_co_u32_e32 v8, vcc, 0x28000, v8
	s_nop 1
	v_addc_co_u32_e32 v9, vcc, 0, v9, vcc
	global_load_dword v5, v[8:9], off nt
.LBB0_900:
	s_or_b64 exec, exec, s[10:11]
	s_and_saveexec_b64 s[10:11], s[4:5]
	s_cbranch_execz .LBB0_902
	v_or_b32_e32 v6, 48, v10
	v_ashrrev_i32_e32 v7, 31, v6
	v_lshlrev_b64 v[6:7], 12, v[6:7]
	v_lshl_add_u64 v[6:7], v[12:13], 0, v[6:7]
	global_load_dword v6, v[6:7], off nt
.LBB0_902:
	s_or_b64 exec, exec, s[10:11]
	v_mov_b32_e32 v9, 0
	v_mov_b32_e32 v7, 0
	s_and_saveexec_b64 s[10:11], s[4:5]
	s_cbranch_execz .LBB0_904
	v_lshlrev_b64 v[10:11], 12, v[10:11]
	v_lshl_add_u64 v[10:11], v[12:13], 0, v[10:11]
	v_add_co_u32_e32 v10, vcc, 0x38000, v10
	s_nop 1
	v_addc_co_u32_e32 v11, vcc, 0, v11, vcc
	global_load_dword v7, v[10:11], off nt

; DI void tr_weight(const float* W, bf16_t* Wt, const int K, const int N, const int ntn, const int drow_off, const int gu, const int rot, ldsp lds, int tid, const int G, const int lb) {
;     ...
;   while (task < ntiles) {
; #pragma unroll
;     for (int i = 0; i < 8; ++i) tile[(kb + 8 * i) * 65 + nn] = pre[i];
;     const int n0 = (task / ktiles) * 64, k0 = (task % ktiles) * 64;
;     const int nxt = task + G;
;     if (nxt < ntiles) { const int n = (nxt / ktiles) * 64 + nn, k1 = (nxt % ktiles) * 64;
; #pragma unroll
;       for (int i = 0; i < 8; ++i) pre[i] = (n < N) ? W[(size_t)(k1 + kb + 8 * i) * N + n] : 0.f; }
.LBB0_907:
	s_add_i32 s17, s7, s6
	s_cmpk_gt_i32 s17, 0xff
	s_cselect_b64 s[10:11], -1, 0
	s_and_b64 vcc, exec, s[10:11]
	s_waitcnt vmcnt(0)
	ds_write_b32 v23, v0
	ds_write_b32 v23, v1 offset:2080
	ds_write_b32 v23, v2 offset:4160
	ds_write_b32 v23, v3 offset:6240
	ds_write_b32 v23, v4 offset:8320
	ds_write_b32 v23, v5 offset:10400
	ds_write_b32 v23, v6 offset:12480
	ds_write_b32 v23, v7 offset:14560
	s_cbranch_vccnz .LBB0_906
	s_ashr_i32 s12, s17, 31
	s_lshr_b32 s12, s12, 28
	s_add_i32 s12, s17, s12
	s_ashr_i32 s12, s12, 4
	v_lshl_or_b32 v0, s12, 6, v14
	v_add_u32_e32 v1, s14, v22
	s_lshl_b32 s12, s12, 10
	v_subrev_u32_e32 v12, s12, v1
	v_ashrrev_i32_e32 v1, 31, v0
	v_cmp_gt_i32_e32 vcc, s16, v0
	v_lshl_add_u64 v[10:11], v[0:1], 2, s[8:9]
	v_mov_b32_e32 v1, 0
	v_mov_b32_e32 v0, 0
	s_and_saveexec_b64 s[12:13], vcc
	s_cbranch_execz .LBB0_910
	v_ashrrev_i32_e32 v13, 31, v12
	v_lshlrev_b64 v[2:3], 12, v[12:13]
	v_lshl_add_u64 v[2:3], v[10:11], 0, v[2:3]
	global_load_dword v0, v[2:3], off nt

; DI void tr_weight(const float* W, bf16_t* Wt, const int K, const int N, const int ntn, const int drow_off, const int gu, const int rot, ldsp lds, int tid, const int G, const int lb) {
;     ...
;     if (nxt < ntiles) { const int n = (nxt / ktiles) * 64 + nn, k1 = (nxt % ktiles) * 64;
; #pragma unroll
;       for (int i = 0; i < 8; ++i) pre[i] = (n < N) ? W[(size_t)(k1 + kb + 8 * i) * N + n] : 0.f; }
.LBB0_920:
	s_or_b64 exec, exec, s[12:13]
	v_mov_b32_e32 v7, 0
	v_mov_b32_e32 v6, 0
	s_and_saveexec_b64 s[12:13], vcc
	s_cbranch_execz .LBB0_922
	v_add_u32_e32 v24, 48, v12
	v_ashrrev_i32_e32 v25, 31, v24
	v_lshlrev_b64 v[24:25], 12, v[24:25]
	v_lshl_add_u64 v[24:25], v[10:11], 0, v[24:25]
	global_load_dword v6, v[24:25], off nt

; DI void tr_weight(const float* W, bf16_t* Wt, const int K, const int N, const int ntn, const int drow_off, const int gu, const int rot, ldsp lds, int tid, const int G, const int lb) {
;     ...
;   int task = (lb + G - (rot % G)) % G;
;   float pre[8];
;   if (task < ntiles) { const int n = (task / ktiles) * 64 + nn, k0 = (task % ktiles) * 64;
; #pragma unroll
;     for (int i = 0; i < 8; ++i) pre[i] = (n < N) ? W[(size_t)(k0 + kb + 8 * i) * N + n] : 0.f; }
.LBB0_924:
	s_lshr_b32 s4, s3, 24
	s_mul_i32 s4, s4, s0
	s_sub_i32 s4, 0x100, s4
	s_sub_i32 s5, s4, s0
	s_cmp_ge_u32 s4, s0
	s_cselect_b32 s4, s5, s4
	s_sub_i32 s5, s4, s0
	s_cmp_ge_u32 s4, s0
	s_cselect_b32 s4, s5, s4
	s_sub_i32 s4, s1, s4
	s_ashr_i32 s5, s4, 31
	s_abs_i32 s4, s4
	s_mul_hi_u32 s7, s4, s3
	s_mul_i32 s7, s7, s0
	s_sub_i32 s4, s4, s7
	s_sub_i32 s7, s4, s0
	s_cmp_ge_u32 s4, s0
	s_cselect_b32 s4, s7, s4
	s_sub_i32 s7, s4, s0
	s_cmp_ge_u32 s4, s0
	s_cselect_b32 s4, s7, s4
	s_xor_b32 s4, s4, s5
	s_sub_i32 s7, s4, s5
	s_cmpk_gt_i32 s7, 0xff
	s_cbranch_scc1 .LBB0_961
	s_ashr_i32 s4, s7, 31
	s_lshr_b32 s4, s4, 28
	s_load_dwordx2 s[8:9], s[72:73], 0xc0
	s_add_i32 s4, s7, s4
	s_lshl_b32 s5, s4, 2
	s_andn2_b32 s5, s5, 63
	s_and_b32 s4, s4, 0x3fffff0
	s_waitcnt vmcnt(1)
	v_or_b32_e32 v0, s5, v14
	s_sub_i32 s10, s7, s4
	s_movk_i32 s4, 0x400
	v_lshl_or_b32 v8, s10, 6, v18
	v_ashrrev_i32_e32 v1, 31, v0
	v_cmp_gt_i32_e64 s[4:5], s4, v0
	s_waitcnt lgkmcnt(0)
	v_lshl_add_u64 v[10:11], v[0:1], 2, s[8:9]
	v_mov_b32_e32 v1, 0
	v_ashrrev_i32_e32 v9, 31, v8
	v_mov_b32_e32 v0, 0
	s_and_saveexec_b64 s[10:11], s[4:5]
	s_cbranch_execz .LBB0_927
	v_lshlrev_b64 v[2:3], 12, v[8:9]
	v_lshl_add_u64 v[2:3], v[10:11], 0, v[2:3]
	global_load_dword v0, v[2:3], off nt
.LBB0_927:
	s_or_b64 exec, exec, s[10:11]
	s_and_saveexec_b64 s[10:11], s[4:5]
	s_cbranch_execz .LBB0_929
	v_lshlrev_b64 v[2:3], 12, v[8:9]
	v_lshl_add_u64 v[2:3], v[10:11], 0, v[2:3]
	v_add_co_u32_e32 v2, vcc, 0x8000, v2
	s_nop 1
	v_addc_co_u32_e32 v3, vcc, 0, v3, vcc
	global_load_dword v1, v[2:3], off nt
.LBB0_929:
	s_or_b64 exec, exec, s[10:11]
	v_mov_b32_e32 v3, 0
	v_mov_b32_e32 v2, 0
	s_and_saveexec_b64 s[10:11], s[4:5]
	s_cbranch_execz .LBB0_931
	v_or_b32_e32 v4, 16, v8
	v_ashrrev_i32_e32 v5, 31, v4
	v_lshlrev_b64 v[4:5], 12, v[4:5]
	v_lshl_add_u64 v[4:5], v[10:11], 0, v[4:5]
	global_load_dword v2, v[4:5], off nt
.LBB0_931:
	s_or_b64 exec, exec, s[10:11]
	s_and_saveexec_b64 s[10:11], s[4:5]
	s_cbranch_execz .LBB0_933
	v_lshlrev_b64 v[4:5], 12, v[8:9]
	v_lshl_add_u64 v[4:5], v[10:11], 0, v[4:5]
	v_add_co_u32_e32 v4, vcc, 0x18000, v4
	s_nop 1
	v_addc_co_u32_e32 v5, vcc, 0, v5, vcc
	global_load_dword v3, v[4:5], off nt
.LBB0_933:
	s_or_b64 exec, exec, s[10:11]
	v_mov_b32_e32 v5, 0
	v_mov_b32_e32 v4, 0
	s_and_saveexec_b64 s[10:11], s[4:5]
	s_cbranch_execz .LBB0_935
	v_or_b32_e32 v6, 32, v8
	v_ashrrev_i32_e32 v7, 31, v6
	v_lshlrev_b64 v[6:7], 12, v[6:7]
	v_lshl_add_u64 v[6:7], v[10:11], 0, v[6:7]
	global_load_dword v4, v[6:7], off nt
.LBB0_935:
	s_or_b64 exec, exec, s[10:11]
	s_and_saveexec_b64 s[10:11], s[4:5]
	s_cbranch_execz .LBB0_937
	v_lshlrev_b64 v[6:7], 12, v[8:9]
	v_lshl_add_u64 v[6:7], v[10:11], 0, v[6:7]
	v_add_co_u32_e32 v6, vcc, 0x28000, v6
	s_nop 1
	v_addc_co_u32_e32 v7, vcc, 0, v7, vcc
	global_load_dword v5, v[6:7], off nt
.LBB0_937:
	s_or_b64 exec, exec, s[10:11]
	v_mov_b32_e32 v7, 0
	v_mov_b32_e32 v6, 0
	s_and_saveexec_b64 s[10:11], s[4:5]
	s_cbranch_execz .LBB0_939
	v_or_b32_e32 v12, 48, v8
	v_ashrrev_i32_e32 v13, 31, v12
	v_lshlrev_b64 v[12:13], 12, v[12:13]
	v_lshl_add_u64 v[12:13], v[10:11], 0, v[12:13]
	global_load_dword v6, v[12:13], off nt
.LBB0_939:
	s_or_b64 exec, exec, s[10:11]
	s_and_saveexec_b64 s[10:11], s[4:5]
	s_cbranch_execz .LBB0_941
	v_lshlrev_b64 v[8:9], 12, v[8:9]
	v_lshl_add_u64 v[8:9], v[10:11], 0, v[8:9]
	v_add_co_u32_e32 v8, vcc, 0x38000, v8
	s_nop 1
	v_addc_co_u32_e32 v9, vcc, 0, v9, vcc
	global_load_dword v7, v[8:9], off nt

; DI void tr_weight(const float* W, bf16_t* Wt, const int K, const int N, const int ntn, const int drow_off, const int gu, const int rot, ldsp lds, int tid, const int G, const int lb) {
;     ...
;   int task = (lb + G - (rot % G)) % G;
;   float pre[8];
;   if (task < ntiles) { const int n = (task / ktiles) * 64 + nn, k0 = (task % ktiles) * 64;
; #pragma unroll
;     for (int i = 0; i < 8; ++i) pre[i] = (n < N) ? W[(size_t)(k0 + kb + 8 * i) * N + n] : 0.f; }
.LBB0_961:
	s_lshr_b32 s4, s3, 23
	s_mul_i32 s4, s4, s0
	s_sub_i32 s4, 0x200, s4
	s_sub_i32 s5, s4, s0
	s_cmp_ge_u32 s4, s0
	s_cselect_b32 s4, s5, s4
	s_sub_i32 s5, s4, s0
	s_cmp_ge_u32 s4, s0
	s_cselect_b32 s4, s5, s4
	s_sub_i32 s4, s1, s4
	s_ashr_i32 s5, s4, 31
	s_abs_i32 s4, s4
	s_mul_hi_u32 s7, s4, s3
	s_mul_i32 s7, s7, s0
	s_sub_i32 s4, s4, s7
	s_sub_i32 s7, s4, s0
	s_cmp_ge_u32 s4, s0
	s_cselect_b32 s4, s7, s4
	s_sub_i32 s7, s4, s0
	s_cmp_ge_u32 s4, s0
	s_cselect_b32 s4, s7, s4
	s_xor_b32 s4, s4, s5
	s_sub_i32 s7, s4, s5
	s_cmpk_gt_i32 s7, 0xff
	s_cbranch_scc1 .LBB0_998
	s_ashr_i32 s4, s7, 31
	s_lshr_b32 s4, s4, 28
	s_load_dwordx2 s[8:9], s[72:73], 0xd8
	s_add_i32 s4, s7, s4
	s_lshl_b32 s5, s4, 2
	s_andn2_b32 s5, s5, 63
	s_and_b32 s4, s4, 0x3fffff0
	s_waitcnt vmcnt(1)
	v_or_b32_e32 v0, s5, v14
	s_sub_i32 s10, s7, s4
	s_movk_i32 s4, 0x400
	v_lshl_or_b32 v8, s10, 6, v18
	v_ashrrev_i32_e32 v1, 31, v0
	v_cmp_gt_i32_e64 s[4:5], s4, v0
	s_waitcnt lgkmcnt(0)
	v_lshl_add_u64 v[10:11], v[0:1], 2, s[8:9]
	v_mov_b32_e32 v1, 0
	v_ashrrev_i32_e32 v9, 31, v8
	v_mov_b32_e32 v0, 0
	s_and_saveexec_b64 s[10:11], s[4:5]
	s_cbranch_execz .LBB0_964
	v_lshlrev_b64 v[2:3], 12, v[8:9]
	v_lshl_add_u64 v[2:3], v[10:11], 0, v[2:3]
	global_load_dword v0, v[2:3], off nt

; DI void tr_weight(const float* W, bf16_t* Wt, const int K, const int N, const int ntn, const int drow_off, const int gu, const int rot, ldsp lds, int tid, const int G, const int lb) {
;     ...
;   int task = (lb + G - (rot % G)) % G;
;   float pre[8];
;   if (task < ntiles) { const int n = (task / ktiles) * 64 + nn, k0 = (task % ktiles) * 64;
; #pragma unroll
;     for (int i = 0; i < 8; ++i) pre[i] = (n < N) ? W[(size_t)(k0 + kb + 8 * i) * N + n] : 0.f; }
.LBB0_998:
	s_mul_hi_u32 s4, s3, 0x300
	s_add_u32 s8, s42, 0x1080000
	s_mul_i32 s4, s4, s0
	s_addc_u32 s9, s43, 0
	s_sub_i32 s4, 0x300, s4
	s_sub_i32 s5, s4, s0
	s_cmp_ge_u32 s4, s0
	s_cselect_b32 s4, s5, s4
	s_sub_i32 s5, s4, s0
	s_cmp_ge_u32 s4, s0
	s_cselect_b32 s4, s5, s4
	s_sub_i32 s4, s1, s4
	s_ashr_i32 s5, s4, 31
	s_abs_i32 s4, s4
	s_mul_hi_u32 s7, s4, s3
	s_mul_i32 s7, s7, s0
	s_sub_i32 s4, s4, s7
	s_sub_i32 s7, s4, s0
	s_cmp_ge_u32 s4, s0
	s_cselect_b32 s4, s7, s4
	s_sub_i32 s7, s4, s0
	s_cmp_ge_u32 s4, s0
	s_cselect_b32 s4, s7, s4
	s_xor_b32 s4, s4, s5
	s_sub_i32 s14, s4, s5
	s_cmpk_gt_i32 s14, 0x2bf
	s_mul_i32 s7, s6, 0x2c000
	s_cbranch_scc1 .LBB0_1035
	s_ashr_i32 s4, s14, 31
	s_lshr_b32 s4, s4, 28
	s_add_i32 s4, s14, s4
	s_lshl_b32 s5, s4, 2
	s_andn2_b32 s5, s5, 63
	s_waitcnt vmcnt(1)
	v_or_b32_e32 v0, s5, v14
	s_and_b32 s4, s4, 0x3fffff0
	s_sub_i32 s10, s14, s4
	s_movk_i32 s12, 0xb00
	v_ashrrev_i32_e32 v1, 31, v0
	v_cmp_gt_i32_e64 s[4:5], s12, v0
	v_lshl_or_b32 v10, s10, 6, v18
	v_lshl_add_u64 v[8:9], v[0:1], 2, s[24:25]
	v_mov_b32_e32 v1, 0
	v_mov_b32_e32 v0, 0
	s_and_saveexec_b64 s[10:11], s[4:5]
	s_cbranch_execz .LBB0_1001
	v_mul_lo_u32 v2, v10, s12
	v_ashrrev_i32_e32 v3, 31, v2
	v_lshl_add_u64 v[2:3], v[2:3], 2, v[8:9]
	global_load_dword v0, v[2:3], off nt
.LBB0_1001:
	s_or_b64 exec, exec, s[10:11]
	s_and_saveexec_b64 s[10:11], s[4:5]
	s_cbranch_execz .LBB0_1003
	v_mul_lo_u32 v2, v10, s12
	v_ashrrev_i32_e32 v3, 31, v2
	v_lshl_add_u64 v[2:3], v[2:3], 2, v[8:9]
	v_add_co_u32_e32 v2, vcc, 0x16000, v2
	s_nop 1
	v_addc_co_u32_e32 v3, vcc, 0, v3, vcc
	global_load_dword v1, v[2:3], off nt
.LBB0_1003:
	s_or_b64 exec, exec, s[10:11]
	v_mov_b32_e32 v3, 0
	v_mov_b32_e32 v2, 0
	s_and_saveexec_b64 s[10:11], s[4:5]
	s_cbranch_execz .LBB0_1005
	v_mul_lo_u32 v4, v10, s12
	v_ashrrev_i32_e32 v5, 31, v4
	v_lshl_add_u64 v[4:5], v[4:5], 2, v[8:9]
	v_add_co_u32_e32 v4, vcc, 0x2c000, v4
	s_nop 1
	v_addc_co_u32_e32 v5, vcc, 0, v5, vcc
	global_load_dword v2, v[4:5], off nt
.LBB0_1005:
	s_or_b64 exec, exec, s[10:11]
	s_and_saveexec_b64 s[10:11], s[4:5]
	s_cbranch_execz .LBB0_1007
	v_mul_lo_u32 v4, v10, s12
	v_ashrrev_i32_e32 v5, 31, v4
	v_lshl_add_u64 v[4:5], v[4:5], 2, v[8:9]
	v_add_co_u32_e32 v4, vcc, 0x42000, v4
	s_nop 1
	v_addc_co_u32_e32 v5, vcc, 0, v5, vcc
	global_load_dword v3, v[4:5], off nt
.LBB0_1007:
	s_or_b64 exec, exec, s[10:11]
	v_mov_b32_e32 v5, 0
	v_mov_b32_e32 v4, 0
	s_and_saveexec_b64 s[10:11], s[4:5]
	s_cbranch_execz .LBB0_1009
	v_mul_lo_u32 v6, v10, s12
	v_ashrrev_i32_e32 v7, 31, v6
	v_lshl_add_u64 v[6:7], v[6:7], 2, v[8:9]
	v_add_co_u32_e32 v6, vcc, 0x58000, v6
	s_nop 1
	v_addc_co_u32_e32 v7, vcc, 0, v7, vcc
	global_load_dword v4, v[6:7], off nt
.LBB0_1009:
	s_or_b64 exec, exec, s[10:11]
	s_and_saveexec_b64 s[10:11], s[4:5]
	s_cbranch_execz .LBB0_1011
	v_mul_lo_u32 v6, v10, s12
	v_ashrrev_i32_e32 v7, 31, v6
	v_lshl_add_u64 v[6:7], v[6:7], 2, v[8:9]
	v_add_co_u32_e32 v6, vcc, 0x6e000, v6
	s_nop 1
	v_addc_co_u32_e32 v7, vcc, 0, v7, vcc
	global_load_dword v5, v[6:7], off nt
.LBB0_1011:
	s_or_b64 exec, exec, s[10:11]
	v_mov_b32_e32 v7, 0
	v_mov_b32_e32 v6, 0
	s_and_saveexec_b64 s[10:11], s[4:5]
	s_cbranch_execz .LBB0_1013
	v_mul_lo_u32 v12, v10, s12
	v_ashrrev_i32_e32 v13, 31, v12
	v_lshl_add_u64 v[12:13], v[12:13], 2, v[8:9]
	v_add_co_u32_e32 v12, vcc, 0x84000, v12
	s_nop 1
	v_addc_co_u32_e32 v13, vcc, 0, v13, vcc
	global_load_dword v6, v[12:13], off nt
.LBB0_1013:
	s_or_b64 exec, exec, s[10:11]
	s_and_saveexec_b64 s[10:11], s[4:5]
	s_cbranch_execz .LBB0_1015
	s_movk_i32 s4, 0xb00
	v_mul_lo_u32 v10, v10, s4
	v_ashrrev_i32_e32 v11, 31, v10
	v_lshl_add_u64 v[8:9], v[10:11], 2, v[8:9]
	v_add_co_u32_e32 v8, vcc, 0x9a000, v8
	s_nop 1
	v_addc_co_u32_e32 v9, vcc, 0, v9, vcc
	global_load_dword v7, v[8:9], off nt

; DI void tr_weight(const float* W, bf16_t* Wt, const int K, const int N, const int ntn, const int drow_off, const int gu, const int rot, ldsp lds, int tid, const int G, const int lb) {
;     ...
;   int task = (lb + G - (rot % G)) % G;
;   float pre[8];
;   if (task < ntiles) { const int n = (task / ktiles) * 64 + nn, k0 = (task % ktiles) * 64;
; #pragma unroll
;     for (int i = 0; i < 8; ++i) pre[i] = (n < N) ? W[(size_t)(k0 + kb + 8 * i) * N + n] : 0.f; }
;   while (task < ntiles) {
; #pragma unroll
;     for (int i = 0; i < 8; ++i) tile[(kb + 8 * i) * 65 + nn] = pre[i];
;     const int n0 = (task / ktiles) * 64, k0 = (task % ktiles) * 64;
;     const int nxt = task + G;
;     if (nxt < ntiles) { const int n = (nxt / ktiles) * 64 + nn, k1 = (nxt % ktiles) * 64;
; #pragma unroll
;       for (int i = 0; i < 8; ++i) pre[i] = (n < N) ? W[(size_t)(k1 + kb + 8 * i) * N + n] : 0.f; }
.LBB0_1018:
	s_add_i32 s18, s14, s6
	s_cmpk_gt_i32 s18, 0x2bf
	s_cselect_b64 s[10:11], -1, 0
	s_and_b64 vcc, exec, s[10:11]
	s_waitcnt vmcnt(0)
	ds_write_b32 v23, v0
	ds_write_b32 v23, v1 offset:2080
	ds_write_b32 v23, v2 offset:4160
	ds_write_b32 v23, v3 offset:6240
	ds_write_b32 v23, v4 offset:8320
	ds_write_b32 v23, v5 offset:10400
	ds_write_b32 v23, v6 offset:12480
	ds_write_b32 v23, v7 offset:14560
	s_cbranch_vccnz .LBB0_1017
	s_ashr_i32 s4, s18, 31
	s_lshr_b32 s4, s4, 28
	s_add_i32 s4, s18, s4
	s_ashr_i32 s12, s4, 4
	v_lshl_or_b32 v0, s12, 6, v14
	v_ashrrev_i32_e32 v1, 31, v0
	s_mul_i32 s12, s12, 0xffd40000
	v_cmp_gt_i32_e64 s[4:5], s17, v0
	v_lshl_add_u64 v[10:11], v[0:1], 2, s[24:25]
	v_mov_b32_e32 v1, 0
	v_add_u32_e32 v12, s12, v22
	v_mov_b32_e32 v0, 0
	s_and_saveexec_b64 s[12:13], s[4:5]
	s_cbranch_execz .LBB0_1021
	v_ashrrev_i32_e32 v13, 31, v12
	v_lshl_add_u64 v[2:3], v[12:13], 2, v[10:11]
	global_load_dword v0, v[2:3], off nt
.LBB0_1021:
	s_or_b64 exec, exec, s[12:13]
	s_and_saveexec_b64 s[12:13], s[4:5]
	s_cbranch_execz .LBB0_1023
	v_ashrrev_i32_e32 v13, 31, v12
	v_lshl_add_u64 v[2:3], v[12:13], 2, v[10:11]
	v_add_co_u32_e32 v2, vcc, 0x16000, v2
	s_nop 1
	v_addc_co_u32_e32 v3, vcc, 0, v3, vcc
	global_load_dword v1, v[2:3], off nt
.LBB0_1023:
	s_or_b64 exec, exec, s[12:13]
	v_mov_b32_e32 v3, 0
	v_mov_b32_e32 v2, 0
	s_and_saveexec_b64 s[12:13], s[4:5]
	s_cbranch_execz .LBB0_1025
	v_ashrrev_i32_e32 v13, 31, v12
	v_lshl_add_u64 v[4:5], v[12:13], 2, v[10:11]
	v_add_co_u32_e32 v4, vcc, 0x2c000, v4
	s_nop 1
	v_addc_co_u32_e32 v5, vcc, 0, v5, vcc
	global_load_dword v2, v[4:5], off nt
.LBB0_1025:
	s_or_b64 exec, exec, s[12:13]
	s_and_saveexec_b64 s[12:13], s[4:5]
	s_cbranch_execz .LBB0_1027
	v_ashrrev_i32_e32 v13, 31, v12
	v_lshl_add_u64 v[4:5], v[12:13], 2, v[10:11]
	v_add_co_u32_e32 v4, vcc, 0x42000, v4
	s_nop 1
	v_addc_co_u32_e32 v5, vcc, 0, v5, vcc
	global_load_dword v3, v[4:5], off nt
.LBB0_1027:
	s_or_b64 exec, exec, s[12:13]
	v_mov_b32_e32 v5, 0
	v_mov_b32_e32 v4, 0
	s_and_saveexec_b64 s[12:13], s[4:5]
	s_cbranch_execz .LBB0_1029
	v_ashrrev_i32_e32 v13, 31, v12
	v_lshl_add_u64 v[6:7], v[12:13], 2, v[10:11]
	v_add_co_u32_e32 v6, vcc, 0x58000, v6
	s_nop 1
	v_addc_co_u32_e32 v7, vcc, 0, v7, vcc
	global_load_dword v4, v[6:7], off nt
.LBB0_1029:
	s_or_b64 exec, exec, s[12:13]
	s_and_saveexec_b64 s[12:13], s[4:5]
	s_cbranch_execz .LBB0_1031
	v_ashrrev_i32_e32 v13, 31, v12
	v_lshl_add_u64 v[6:7], v[12:13], 2, v[10:11]
	v_add_co_u32_e32 v6, vcc, 0x6e000, v6
	s_nop 1
	v_addc_co_u32_e32 v7, vcc, 0, v7, vcc
	global_load_dword v5, v[6:7], off nt
.LBB0_1031:
	s_or_b64 exec, exec, s[12:13]
	v_mov_b32_e32 v7, 0
	v_mov_b32_e32 v6, 0
	s_and_saveexec_b64 s[12:13], s[4:5]
	s_cbranch_execz .LBB0_1033
	v_ashrrev_i32_e32 v13, 31, v12
	v_lshl_add_u64 v[24:25], v[12:13], 2, v[10:11]
	v_add_co_u32_e32 v24, vcc, 0x84000, v24
	s_nop 1
	v_addc_co_u32_e32 v25, vcc, 0, v25, vcc
	global_load_dword v6, v[24:25], off nt
.LBB0_1033:
	s_or_b64 exec, exec, s[12:13]
	s_and_saveexec_b64 s[12:13], s[4:5]
	s_cbranch_execz .LBB0_1016
	v_ashrrev_i32_e32 v13, 31, v12
	v_lshl_add_u64 v[10:11], v[12:13], 2, v[10:11]
	v_add_co_u32_e32 v10, vcc, 0x9a000, v10
	s_nop 1
	v_addc_co_u32_e32 v11, vcc, 0, v11, vcc
	global_load_dword v7, v[10:11], off nt
	s_branch .LBB0_1016
.LBB0_1035:
	s_mul_hi_u32 s4, s3, 0x5c0
	s_mul_i32 s4, s4, s0
	s_sub_i32 s4, 0x5c0, s4
	s_sub_i32 s5, s4, s0
	s_cmp_ge_u32 s4, s0
	s_cselect_b32 s4, s5, s4
	s_sub_i32 s5, s4, s0
	s_cmp_ge_u32 s4, s0
	s_cselect_b32 s4, s5, s4
	s_sub_i32 s4, s1, s4
	s_ashr_i32 s5, s4, 31
	s_abs_i32 s4, s4
	s_mul_hi_u32 s10, s4, s3
	s_mul_i32 s10, s10, s0
	s_sub_i32 s4, s4, s10
	s_sub_i32 s10, s4, s0
	s_cmp_ge_u32 s4, s0
	s_cselect_b32 s4, s10, s4
	s_sub_i32 s10, s4, s0
	s_cmp_ge_u32 s4, s0
	s_cselect_b32 s4, s10, s4
	s_xor_b32 s4, s4, s5
	s_sub_i32 s14, s4, s5
	s_cmpk_gt_i32 s14, 0x2bf
	s_cbranch_scc1 .LBB0_1072
	s_ashr_i32 s4, s14, 31
	s_lshr_b32 s4, s4, 28
	s_add_i32 s4, s14, s4
	s_lshl_b32 s5, s4, 2
	s_andn2_b32 s5, s5, 63
	s_waitcnt vmcnt(1)
	v_or_b32_e32 v0, s5, v14
	s_and_b32 s4, s4, 0x3fffff0
	s_sub_i32 s10, s14, s4
	s_movk_i32 s12, 0xb00
	v_ashrrev_i32_e32 v1, 31, v0
	v_cmp_gt_i32_e64 s[4:5], s12, v0
	v_lshl_or_b32 v10, s10, 6, v18
	v_lshl_add_u64 v[8:9], v[0:1], 2, s[26:27]
	v_mov_b32_e32 v1, 0
	v_mov_b32_e32 v0, 0
	s_and_saveexec_b64 s[10:11], s[4:5]
	s_cbranch_execz .LBB0_1038
	v_mul_lo_u32 v2, v10, s12
	v_ashrrev_i32_e32 v3, 31, v2
	v_lshl_add_u64 v[2:3], v[2:3], 2, v[8:9]
	global_load_dword v0, v[2:3], off nt

; DI void tr_weight(const float* W, bf16_t* Wt, const int K, const int N, const int ntn, const int drow_off, const int gu, const int rot, ldsp lds, int tid, const int G, const int lb) {
;     ...
;   while (task < ntiles) {
; #pragma unroll
;     for (int i = 0; i < 8; ++i) tile[(kb + 8 * i) * 65 + nn] = pre[i];
;     const int n0 = (task / ktiles) * 64, k0 = (task % ktiles) * 64;
;     const int nxt = task + G;
;     if (nxt < ntiles) { const int n = (nxt / ktiles) * 64 + nn, k1 = (nxt % ktiles) * 64;
; #pragma unroll
;       for (int i = 0; i < 8; ++i) pre[i] = (n < N) ? W[(size_t)(k1 + kb + 8 * i) * N + n] : 0.f; }
.LBB0_1055:
	s_add_i32 s18, s14, s6
	s_cmpk_gt_i32 s18, 0x2bf
	s_cselect_b64 s[10:11], -1, 0
	s_and_b64 vcc, exec, s[10:11]
	s_waitcnt vmcnt(0)
	ds_write_b32 v23, v0
	ds_write_b32 v23, v1 offset:2080
	ds_write_b32 v23, v2 offset:4160
	ds_write_b32 v23, v3 offset:6240
	ds_write_b32 v23, v4 offset:8320
	ds_write_b32 v23, v5 offset:10400
	ds_write_b32 v23, v6 offset:12480
	ds_write_b32 v23, v7 offset:14560
	s_cbranch_vccnz .LBB0_1054
	s_ashr_i32 s4, s18, 31
	s_lshr_b32 s4, s4, 28
	s_add_i32 s4, s18, s4
	s_ashr_i32 s12, s4, 4
	v_lshl_or_b32 v0, s12, 6, v14
	v_ashrrev_i32_e32 v1, 31, v0
	s_mul_i32 s12, s12, 0xffd40000
	v_cmp_gt_i32_e64 s[4:5], s17, v0
	v_lshl_add_u64 v[10:11], v[0:1], 2, s[26:27]
	v_mov_b32_e32 v1, 0
	v_add_u32_e32 v12, s12, v22
	v_mov_b32_e32 v0, 0
	s_and_saveexec_b64 s[12:13], s[4:5]
	s_cbranch_execz .LBB0_1058
	v_ashrrev_i32_e32 v13, 31, v12
	v_lshl_add_u64 v[2:3], v[12:13], 2, v[10:11]
	global_load_dword v0, v[2:3], off nt

; DI void tr_weight(const float* W, bf16_t* Wt, const int K, const int N, const int ntn, const int drow_off, const int gu, const int rot, ldsp lds, int tid, const int G, const int lb) {
;     ...
;   int task = (lb + G - (rot % G)) % G;
;   float pre[8];
;   if (task < ntiles) { const int n = (task / ktiles) * 64 + nn, k0 = (task % ktiles) * 64;
; #pragma unroll
;     for (int i = 0; i < 8; ++i) pre[i] = (n < N) ? W[(size_t)(k0 + kb + 8 * i) * N + n] : 0.f; }
.LBB0_1072:
	s_mul_hi_u32 s4, s3, 0x880
	s_mul_i32 s4, s4, s0
	s_sub_i32 s4, 0x880, s4
	s_sub_i32 s5, s4, s0
	s_cmp_ge_u32 s4, s0
	s_cselect_b32 s4, s5, s4
	s_sub_i32 s5, s4, s0
	s_cmp_ge_u32 s4, s0
	s_cselect_b32 s4, s5, s4
	s_sub_i32 s1, s1, s4
	s_ashr_i32 s4, s1, 31
	s_abs_i32 s1, s1
	s_mul_hi_u32 s3, s1, s3
	s_mul_i32 s3, s3, s0
	s_sub_i32 s1, s1, s3
	s_sub_i32 s3, s1, s0
	s_cmp_ge_u32 s1, s0
	s_cselect_b32 s1, s3, s1
	s_sub_i32 s3, s1, s0
	s_cmp_ge_u32 s1, s0
	s_cselect_b32 s0, s3, s1
	s_xor_b32 s0, s0, s4
	s_sub_i32 s0, s0, s4
	s_cmpk_gt_i32 s0, 0x2bf
	s_cbranch_scc1 .LBB0_1109
	s_mul_hi_i32 s1, s0, 0x2e8ba2e9
	s_lshr_b32 s3, s1, 31
	s_ashr_i32 s1, s1, 3
	s_add_i32 s1, s1, s3
	s_waitcnt vmcnt(1)
	v_lshl_or_b32 v0, s1, 6, v14
	s_mul_i32 s1, s1, 44
	s_sub_i32 s1, s0, s1
	v_readlane_b32 s12, v248, 10
	s_movk_i32 s3, 0x400
	v_lshl_or_b32 v8, s1, 6, v18
	v_ashrrev_i32_e32 v1, 31, v0
	v_readlane_b32 s16, v248, 14
	v_readlane_b32 s17, v248, 15
	v_cmp_gt_i32_e64 s[4:5], s3, v0
	v_ashrrev_i32_e32 v9, 31, v8
	v_lshl_add_u64 v[10:11], v[0:1], 2, s[16:17]
	v_mov_b32_e32 v1, 0
	v_mov_b32_e32 v0, 0
	v_readlane_b32 s13, v248, 11
	v_readlane_b32 s14, v248, 12
	v_readlane_b32 s15, v248, 13
	v_readlane_b32 s18, v248, 16
	v_readlane_b32 s19, v248, 17
	s_and_saveexec_b64 s[8:9], s[4:5]
	s_cbranch_execz .LBB0_1075
	v_lshlrev_b64 v[2:3], 12, v[8:9]
	v_lshl_add_u64 v[2:3], v[10:11], 0, v[2:3]
	global_load_dword v0, v[2:3], off nt

; DI void tr_weight(const float* W, bf16_t* Wt, const int K, const int N, const int ntn, const int drow_off, const int gu, const int rot, ldsp lds, int tid, const int G, const int lb) {
;     ...
;   if (task < ntiles) { const int n = (task / ktiles) * 64 + nn, k0 = (task % ktiles) * 64;
; #pragma unroll
;     for (int i = 0; i < 8; ++i) pre[i] = (n < N) ? W[(size_t)(k0 + kb + 8 * i) * N + n] : 0.f; }
.LBB0_1077:
	s_or_b64 exec, exec, s[8:9]
	v_mov_b32_e32 v3, 0
	v_mov_b32_e32 v2, 0
	s_and_saveexec_b64 s[8:9], s[4:5]
	s_cbranch_execz .LBB0_1079
	v_or_b32_e32 v4, 16, v8
	v_ashrrev_i32_e32 v5, 31, v4
	v_lshlrev_b64 v[4:5], 12, v[4:5]
	v_lshl_add_u64 v[4:5], v[10:11], 0, v[4:5]
	global_load_dword v2, v[4:5], off nt

; DI void tr_weight(const float* W, bf16_t* Wt, const int K, const int N, const int ntn, const int drow_off, const int gu, const int rot, ldsp lds, int tid, const int G, const int lb) {
;     ...
;   if (task < ntiles) { const int n = (task / ktiles) * 64 + nn, k0 = (task % ktiles) * 64;
; #pragma unroll
;     for (int i = 0; i < 8; ++i) pre[i] = (n < N) ? W[(size_t)(k0 + kb + 8 * i) * N + n] : 0.f; }
.LBB0_1081:
	s_or_b64 exec, exec, s[8:9]
	v_mov_b32_e32 v5, 0
	v_mov_b32_e32 v4, 0
	s_and_saveexec_b64 s[8:9], s[4:5]
	s_cbranch_execz .LBB0_1083
	v_or_b32_e32 v6, 32, v8
	v_ashrrev_i32_e32 v7, 31, v6
	v_lshlrev_b64 v[6:7], 12, v[6:7]
	v_lshl_add_u64 v[6:7], v[10:11], 0, v[6:7]
	global_load_dword v4, v[6:7], off nt

; DI void tr_weight(const float* W, bf16_t* Wt, const int K, const int N, const int ntn, const int drow_off, const int gu, const int rot, ldsp lds, int tid, const int G, const int lb) {
;     ...
;   if (task < ntiles) { const int n = (task / ktiles) * 64 + nn, k0 = (task % ktiles) * 64;
; #pragma unroll
;     for (int i = 0; i < 8; ++i) pre[i] = (n < N) ? W[(size_t)(k0 + kb + 8 * i) * N + n] : 0.f; }
.LBB0_1085:
	s_or_b64 exec, exec, s[8:9]
	v_mov_b32_e32 v7, 0
	v_mov_b32_e32 v6, 0
	s_and_saveexec_b64 s[8:9], s[4:5]
	s_cbranch_execz .LBB0_1087
	v_or_b32_e32 v12, 48, v8
	v_ashrrev_i32_e32 v13, 31, v12
	v_lshlrev_b64 v[12:13], 12, v[12:13]
	v_lshl_add_u64 v[12:13], v[10:11], 0, v[12:13]
	global_load_dword v6, v[12:13], off nt

; DI void tr_weight(const float* W, bf16_t* Wt, const int K, const int N, const int ntn, const int drow_off, const int gu, const int rot, ldsp lds, int tid, const int G, const int lb) {
;     ...
;   while (task < ntiles) {
; #pragma unroll
;     for (int i = 0; i < 8; ++i) tile[(kb + 8 * i) * 65 + nn] = pre[i];
;     const int n0 = (task / ktiles) * 64, k0 = (task % ktiles) * 64;
;     const int nxt = task + G;
;     if (nxt < ntiles) { const int n = (nxt / ktiles) * 64 + nn, k1 = (nxt % ktiles) * 64;
; #pragma unroll
;       for (int i = 0; i < 8; ++i) pre[i] = (n < N) ? W[(size_t)(k1 + kb + 8 * i) * N + n] : 0.f; }
.LBB0_1092:
	s_add_i32 s13, s0, s6
	s_cmpk_gt_i32 s13, 0x2bf
	s_cselect_b64 s[8:9], -1, 0
	s_and_b64 vcc, exec, s[8:9]
	s_waitcnt vmcnt(0)
	ds_write_b32 v20, v0
	ds_write_b32 v20, v1 offset:2080
	ds_write_b32 v20, v2 offset:4160
	ds_write_b32 v20, v3 offset:6240
	ds_write_b32 v20, v4 offset:8320
	ds_write_b32 v20, v5 offset:10400
	ds_write_b32 v20, v6 offset:12480
	ds_write_b32 v20, v7 offset:14560
	s_cbranch_vccnz .LBB0_1091
	s_mul_hi_i32 s10, s13, 0x2e8ba2e9
	s_lshr_b32 s11, s10, 31
	s_ashr_i32 s10, s10, 3
	s_add_i32 s10, s10, s11
	v_lshl_or_b32 v0, s10, 6, v14
	s_mulk_i32 s10, 0xf500
	s_add_i32 s10, s10, s1
	v_ashrrev_i32_e32 v1, 31, v0
	v_cmp_gt_i32_e32 vcc, s7, v0
	v_add_u32_e32 v12, s10, v18
	v_lshl_add_u64 v[10:11], v[0:1], 2, s[16:17]
	v_mov_b32_e32 v1, 0
	v_mov_b32_e32 v0, 0
	s_and_saveexec_b64 s[10:11], vcc
	s_cbranch_execz .LBB0_1095
	v_ashrrev_i32_e32 v13, 31, v12
	v_lshlrev_b64 v[2:3], 12, v[12:13]
	v_lshl_add_u64 v[2:3], v[10:11], 0, v[2:3]
	global_load_dword v0, v[2:3], off nt
.LBB0_1095:
	s_or_b64 exec, exec, s[10:11]
	s_and_saveexec_b64 s[10:11], vcc
	s_cbranch_execz .LBB0_1097
	v_add_u32_e32 v2, 8, v12
	v_ashrrev_i32_e32 v3, 31, v2
	v_lshlrev_b64 v[2:3], 12, v[2:3]
	v_lshl_add_u64 v[2:3], v[10:11], 0, v[2:3]
	global_load_dword v1, v[2:3], off nt
.LBB0_1097:
	s_or_b64 exec, exec, s[10:11]
	v_mov_b32_e32 v3, 0
	v_mov_b32_e32 v2, 0
	s_and_saveexec_b64 s[10:11], vcc
	s_cbranch_execz .LBB0_1099
	v_add_u32_e32 v4, 16, v12
	v_ashrrev_i32_e32 v5, 31, v4
	v_lshlrev_b64 v[4:5], 12, v[4:5]
	v_lshl_add_u64 v[4:5], v[10:11], 0, v[4:5]
	global_load_dword v2, v[4:5], off nt
.LBB0_1099:
	s_or_b64 exec, exec, s[10:11]
	s_and_saveexec_b64 s[10:11], vcc
	s_cbranch_execz .LBB0_1101
	v_add_u32_e32 v4, 24, v12
	v_ashrrev_i32_e32 v5, 31, v4
	v_lshlrev_b64 v[4:5], 12, v[4:5]
	v_lshl_add_u64 v[4:5], v[10:11], 0, v[4:5]
	global_load_dword v3, v[4:5], off nt
.LBB0_1101:
	s_or_b64 exec, exec, s[10:11]
	v_mov_b32_e32 v5, 0
	v_mov_b32_e32 v4, 0
	s_and_saveexec_b64 s[10:11], vcc
	s_cbranch_execz .LBB0_1103
	v_add_u32_e32 v6, 32, v12
	v_ashrrev_i32_e32 v7, 31, v6
	v_lshlrev_b64 v[6:7], 12, v[6:7]
	v_lshl_add_u64 v[6:7], v[10:11], 0, v[6:7]
	global_load_dword v4, v[6:7], off nt
.LBB0_1103:
	s_or_b64 exec, exec, s[10:11]
	s_and_saveexec_b64 s[10:11], vcc
	s_cbranch_execz .LBB0_1105
	v_add_u32_e32 v6, 40, v12
	v_ashrrev_i32_e32 v7, 31, v6
	v_lshlrev_b64 v[6:7], 12, v[6:7]
	v_lshl_add_u64 v[6:7], v[10:11], 0, v[6:7]
	global_load_dword v5, v[6:7], off nt
.LBB0_1105:
	s_or_b64 exec, exec, s[10:11]
	v_mov_b32_e32 v7, 0
	v_mov_b32_e32 v6, 0
	s_and_saveexec_b64 s[10:11], vcc
	s_cbranch_execz .LBB0_1107
	v_add_u32_e32 v22, 48, v12
	v_ashrrev_i32_e32 v23, 31, v22
	v_lshlrev_b64 v[22:23], 12, v[22:23]
	v_lshl_add_u64 v[22:23], v[10:11], 0, v[22:23]
	global_load_dword v6, v[22:23], off nt
.LBB0_1107:
	s_or_b64 exec, exec, s[10:11]
	s_and_saveexec_b64 s[10:11], vcc
	s_cbranch_execz .LBB0_1090
	v_add_u32_e32 v12, 56, v12
	v_ashrrev_i32_e32 v13, 31, v12
	v_lshlrev_b64 v[12:13], 12, v[12:13]
	v_lshl_add_u64 v[10:11], v[10:11], 0, v[12:13]
	global_load_dword v7, v[10:11], off nt
	s_branch .LBB0_1090

; __global__ void __launch_bounds__(512, 2) fwd_mega(Params p) {
	.amdhsa_kernel _Z8fwd_mega6Params
		.amdhsa_group_segment_fixed_size 16
		.amdhsa_private_segment_fixed_size 0
		.amdhsa_kernarg_size 536
		.amdhsa_user_sgpr_count 2
		.amdhsa_user_sgpr_dispatch_ptr 0
		.amdhsa_user_sgpr_queue_ptr 0
		.amdhsa_user_sgpr_kernarg_segment_ptr 1
		.amdhsa_user_sgpr_dispatch_id 0
		.amdhsa_user_sgpr_kernarg_preload_length 0
		.amdhsa_user_sgpr_kernarg_preload_offset 0
		.amdhsa_user_sgpr_private_segment_size 0
		.amdhsa_uses_dynamic_stack 0
		.amdhsa_enable_private_segment 0
		.amdhsa_system_sgpr_workgroup_id_x 1
		.amdhsa_system_sgpr_workgroup_id_y 0
		.amdhsa_system_sgpr_workgroup_id_z 0
		.amdhsa_system_sgpr_workgroup_info 0
		.amdhsa_system_vgpr_workitem_id 2
		.amdhsa_next_free_vgpr 256
		.amdhsa_next_free_sgpr 98
		.amdhsa_accum_offset 256
		.amdhsa_reserve_vcc 1
		.amdhsa_float_round_mode_32 0
		.amdhsa_float_round_mode_16_64 0
		.amdhsa_float_denorm_mode_32 3
		.amdhsa_float_denorm_mode_16_64 3
		.amdhsa_dx10_clamp 1
		.amdhsa_ieee_mode 1
		.amdhsa_fp16_overflow 0
		.amdhsa_tg_split 0
		.amdhsa_exception_fp_ieee_invalid_op 0
		.amdhsa_exception_fp_denorm_src 0
		.amdhsa_exception_fp_ieee_div_zero 0
		.amdhsa_exception_fp_ieee_overflow 0
		.amdhsa_exception_fp_ieee_underflow 0
		.amdhsa_exception_fp_ieee_inexact 0
		.amdhsa_exception_int_div_zero 0
	.end_amdhsa_kernel

; __global__ void __launch_bounds__(512, 2) fwd_mega(Params p) {
amdhsa.kernels:
  - .agpr_count:     0
    .args:
      - .offset:         0
        .size:           280
        .value_kind:     by_value
      - .offset:         280
        .size:           4
        .value_kind:     hidden_block_count_x
      - .offset:         284
        .size:           4
        .value_kind:     hidden_block_count_y
      - .offset:         288
        .size:           4
        .value_kind:     hidden_block_count_z
      - .offset:         292
        .size:           2
        .value_kind:     hidden_group_size_x
      - .offset:         294
        .size:           2
        .value_kind:     hidden_group_size_y
      - .offset:         296
        .size:           2
        .value_kind:     hidden_group_size_z
      - .offset:         298
        .size:           2
        .value_kind:     hidden_remainder_x
      - .offset:         300
        .size:           2
        .value_kind:     hidden_remainder_y
      - .offset:         302
        .size:           2
        .value_kind:     hidden_remainder_z
      - .offset:         320
        .size:           8
        .value_kind:     hidden_global_offset_x
      - .offset:         328
        .size:           8
        .value_kind:     hidden_global_offset_y
      - .offset:         336
        .size:           8
        .value_kind:     hidden_global_offset_z
      - .offset:         344
        .size:           2
        .value_kind:     hidden_grid_dims
      - .offset:         368
        .size:           8
        .value_kind:     hidden_multigrid_sync_arg
      - .offset:         400
        .size:           4
        .value_kind:     hidden_dynamic_lds_size
    .group_segment_fixed_size: 16
    .kernarg_segment_align: 8
    .kernarg_segment_size: 536
    .language:       OpenCL C
    .language_version:
      - 2
      - 0
    .max_flat_workgroup_size: 512
    .name:           _Z8fwd_mega6Params
    .private_segment_fixed_size: 0
    .sgpr_count:     104
    .sgpr_spill_count: 24
    .symbol:         _Z8fwd_mega6Params.kd
    .uniform_work_group_size: 1
    .uses_dynamic_stack: false
    .vgpr_count:     256
    .vgpr_spill_count: 0
    .wavefront_size: 64
